# GEMM load segments: wait state between each M0 write and its LDS-DMA provided by the segment's last ds_reads instead of s_nop 0 (15 fewer loader instructions per iteration); on v094
# speedup vs baseline: 1.0078x; 1.0078x over previous
; #define PG8_STAGE(bufoff, gbase, voff) do { _Pragma("unroll") for (int _i = 0; _i < 2; ++_i) \
;         __builtin_amdgcn_global_load_lds((const unsigned*)((const char*)(gbase) + (voff)[_i]), (PG8_LAS unsigned*)(lds + (bufoff) + ldsw + _i * 8192), 16, 0, 0); } while (0)
; #define PG8_LDA(dst, b, h) do { _Pragma("unroll") for (int m = 0; m < 4; ++m) _Pragma("unroll") for (int k = 0; k < 2; ++k) dst[m][k] = *(const PG8_LAS bf16x8*)(lds + PG8_SA(b, h) + aoff + m * 2048 + k * 1024); } while (0)
; #define PG8_LDB(dst, b, h) do { _Pragma("unroll") for (int n = 0; n < 2; ++n) _Pragma("unroll") for (int k = 0; k < 2; ++k) dst[n][k] = *(const PG8_LAS bf16x8*)(lds + PG8_SB(b, h) + boff + n * 2048 + k * 1024); } while (0)
; #define PG8_MMA(ai, bj, At, Bt) do { __builtin_amdgcn_s_setprio(1); _Pragma("unroll") for (int m = 0; m < 4; ++m) _Pragma("unroll") for (int n = 0; n < 2; ++n) _Pragma("unroll") for (int k = 0; k < 2; ++k) \
;         acc[ai][bj][m][n] = __builtin_amdgcn_mfma_f32_16x16x32_bf16(Bt[n][k], At[m][k], acc[ai][bj][m][n], 0, 0, 0); __builtin_amdgcn_s_setprio(0); } while (0)
; #define PG8_WAIT_L(n) asm volatile("s_waitcnt lgkmcnt(" #n ")" ::: "memory")
; template <class Epi, class Sched, bool ALIGN_EPI = false, bool SP2 = false>
; __device__ __forceinline__ void gemm_phase(PG8_LAS unsigned char* lds, const Gemm g, const Sched& S, const Epi& E) {
;     ...
;             const bool last = (t == nt - 2);
;             const char* a1 = cA + (size_t)(t + 1) * kstep;
;             const char* a2 = last ? nA : cA + (size_t)(t + 2) * kstep; const char* b2 = last ? nB : cB + (size_t)(t + 2) * kstep;
;             const char* a3 = a2 + kstep; const char* b3 = b2 + kstep;
;             if (last && has_next) S.a_ready(nxt);
;             if constexpr (SP2) {
;             const int rx = (relax && t == 0) ? 1 : 0;
;             PG8_STAGE(PG8_SA(1, 1), a1 + hstep, voffA); PG8_SCHED; PG8_LDB(B0, 0, 0); PG8_LDB(B1, 0, 1); PG8_SCHED; PG8_LDA(At, 0, 0);
;             PG8_WAIT_V8_UNLESS(rx); PG8_WAIT_L(0); PG8_BAR; PG8_MMA(0, 0, At, B0); PG8_MMA(0, 1, At, B1); PG8_BAR; PG8_SCHED;
;             PG8_STAGE(PG8_SB(0, 0), b2, voffB); PG8_STAGE(PG8_SB(0, 1), b2 + hstep, voffB); PG8_STAGE(PG8_SA(0, 0), a2, voffA); PG8_SCHED; PG8_LDA(At, 0, 1);
;             PG8_WAIT_V8_UNLESS(rx); PG8_WAIT_L(0); PG8_BAR; PG8_MMA(1, 0, At, B0); PG8_MMA(1, 1, At, B1); PG8_BAR; PG8_SCHED;
.LBB0_148:
	s_add_u32 s28, s0, vcc_lo
	s_addc_u32 s29, s1, vcc_hi
	s_add_u32 s30, s28, 0x100
	s_addc_u32 s31, s29, 0
	s_add_u32 s98, s28, 0x40080
	s_addc_u32 s99, s29, 0
	s_add_u32 s61, s58, vcc_lo
	s_addc_u32 s65, s59, vcc_hi
	s_cmp_eq_u32 vcc_lo, 0
	s_cselect_b64 s[28:29], -1, 0
	s_and_b64 s[66:67], s[42:43], s[28:29]
	s_cmpk_eq_i32 vcc_lo, 0x700
	s_cselect_b32 s31, s21, s31
	s_cselect_b32 s30, s34, s30
	s_cselect_b32 s29, s19, s65
	s_cselect_b32 s28, s41, s61
	s_add_i32 s61, 0, 0x10000
	s_add_i32 s65, 0, 0x14000
	v_add_u32_e32 v156, s61, v172
	v_add_u32_e32 v174, s65, v172
	ds_read_b128 v[144:147], v156
	ds_read_b128 v[148:151], v156 offset:1024
	ds_read_b128 v[152:155], v156 offset:2048
	ds_read_b128 v[156:159], v156 offset:3072
	ds_read_b128 v[160:163], v174
	ds_read_b128 v[164:167], v174 offset:1024
	ds_read_b128 v[168:171], v174 offset:2048
	ds_read_b128 v[174:177], v174 offset:3072
	ds_read_b128 v[178:181], v173
	ds_read_b128 v[182:185], v173 offset:1024
	ds_read_b128 v[186:189], v173 offset:2048
	ds_read_b128 v[204:207], v173 offset:3072
	ds_read_b128 v[208:211], v173 offset:4096
	ds_read_b128 v[212:215], v173 offset:5120
	ds_read_b128 v[216:219], v173 offset:6144
	s_add_i32 m0, s9, 0xc000
	s_and_b32 s70, s66, 1
	global_load_lds_dwordx4 v132, s[98:99]
	s_add_i32 m0, s9, 0xe000
	ds_read_b128 v[220:223], v173 offset:7168
	global_load_lds_dwordx4 v136, s[98:99]
	s_cmp_lg_i32 s70, 0
	s_cbranch_scc1 .Lpg8rx0
	s_waitcnt vmcnt(8)
.Lpg8rx0:
	s_waitcnt lgkmcnt(0)
	s_setprio 1
	s_barrier
	v_mfma_f32_16x16x32_bf16 v[124:127], v[144:147], v[178:181], v[124:127]
	v_mfma_f32_16x16x32_bf16 v[120:123], v[152:155], v[178:181], v[120:123]
	v_mfma_f32_16x16x32_bf16 v[108:111], v[144:147], v[186:189], v[108:111]
	v_mfma_f32_16x16x32_bf16 v[104:107], v[152:155], v[186:189], v[104:107]
	v_mfma_f32_16x16x32_bf16 v[92:95], v[144:147], v[208:211], v[92:95]
	v_mfma_f32_16x16x32_bf16 v[88:91], v[152:155], v[208:211], v[88:91]
	v_mfma_f32_16x16x32_bf16 v[76:79], v[144:147], v[216:219], v[76:79]
	v_mfma_f32_16x16x32_bf16 v[72:75], v[152:155], v[216:219], v[72:75]
	v_mfma_f32_16x16x32_bf16 v[124:127], v[148:151], v[182:185], v[124:127]
	v_mfma_f32_16x16x32_bf16 v[120:123], v[156:159], v[182:185], v[120:123]
	v_mfma_f32_16x16x32_bf16 v[108:111], v[148:151], v[204:207], v[108:111]
	v_mfma_f32_16x16x32_bf16 v[104:107], v[156:159], v[204:207], v[104:107]
	v_mfma_f32_16x16x32_bf16 v[92:95], v[148:151], v[212:215], v[92:95]
	v_mfma_f32_16x16x32_bf16 v[88:91], v[156:159], v[212:215], v[88:91]
	v_mfma_f32_16x16x32_bf16 v[76:79], v[148:151], v[220:223], v[76:79]
	v_mfma_f32_16x16x32_bf16 v[72:75], v[156:159], v[220:223], v[72:75]
	v_mfma_f32_16x16x32_bf16 v[116:119], v[160:163], v[178:181], v[116:119]
	v_mfma_f32_16x16x32_bf16 v[112:115], v[168:171], v[178:181], v[112:115]
	v_mfma_f32_16x16x32_bf16 v[100:103], v[160:163], v[186:189], v[100:103]
	v_mfma_f32_16x16x32_bf16 v[96:99], v[168:171], v[186:189], v[96:99]
	v_mfma_f32_16x16x32_bf16 v[84:87], v[160:163], v[208:211], v[84:87]
	v_mfma_f32_16x16x32_bf16 v[80:83], v[168:171], v[208:211], v[80:83]
	v_mfma_f32_16x16x32_bf16 v[68:71], v[160:163], v[216:219], v[68:71]
	v_mfma_f32_16x16x32_bf16 v[64:67], v[168:171], v[216:219], v[64:67]
	v_mfma_f32_16x16x32_bf16 v[116:119], v[164:167], v[182:185], v[116:119]
	v_mfma_f32_16x16x32_bf16 v[112:115], v[174:177], v[182:185], v[112:115]
	v_mfma_f32_16x16x32_bf16 v[100:103], v[164:167], v[204:207], v[100:103]
	v_mfma_f32_16x16x32_bf16 v[96:99], v[174:177], v[204:207], v[96:99]
	v_mfma_f32_16x16x32_bf16 v[84:87], v[164:167], v[212:215], v[84:87]
	v_mfma_f32_16x16x32_bf16 v[80:83], v[174:177], v[212:215], v[80:83]
	v_mfma_f32_16x16x32_bf16 v[68:71], v[164:167], v[220:223], v[68:71]
	v_mfma_f32_16x16x32_bf16 v[64:67], v[174:177], v[220:223], v[64:67]
	s_setprio 0
	s_barrier
	ds_read_b128 v[178:181], v173 offset:16384
	ds_read_b128 v[182:185], v173 offset:17408
	s_add_u32 s66, s28, 0x40000
	s_addc_u32 s67, s29, 0
	s_add_i32 m0, s61, s46
	ds_read_b128 v[186:189], v173 offset:18432
	global_load_lds_dwordx4 v134, s[28:29]
	s_add_i32 m0, m0, 0x2000
	ds_read_b128 v[204:207], v173 offset:19456
	global_load_lds_dwordx4 v138, s[28:29]
	s_add_i32 m0, s65, s46
	ds_read_b128 v[208:211], v173 offset:20480
	global_load_lds_dwordx4 v134, s[66:67]
	s_add_i32 m0, m0, 0x2000
	ds_read_b128 v[212:215], v173 offset:21504
	global_load_lds_dwordx4 v138, s[66:67]
	s_mov_b32 m0, s9
	ds_read_b128 v[216:219], v173 offset:22528
	global_load_lds_dwordx4 v132, s[30:31]
	s_mov_b32 m0, s51
	ds_read_b128 v[220:223], v173 offset:23552
	global_load_lds_dwordx4 v136, s[30:31]
	s_cmp_lg_i32 s70, 0
	s_cbranch_scc1 .Lpg8rx1
	s_waitcnt vmcnt(8)
; #define PG8_STAGE(bufoff, gbase, voff) do { _Pragma("unroll") for (int _i = 0; _i < 2; ++_i) \
;         __builtin_amdgcn_global_load_lds((const unsigned*)((const char*)(gbase) + (voff)[_i]), (PG8_LAS unsigned*)(lds + (bufoff) + ldsw + _i * 8192), 16, 0, 0); } while (0)
; #define PG8_LDA(dst, b, h) do { _Pragma("unroll") for (int m = 0; m < 4; ++m) _Pragma("unroll") for (int k = 0; k < 2; ++k) dst[m][k] = *(const PG8_LAS bf16x8*)(lds + PG8_SA(b, h) + aoff + m * 2048 + k * 1024); } while (0)
; #define PG8_LDB(dst, b, h) do { _Pragma("unroll") for (int n = 0; n < 2; ++n) _Pragma("unroll") for (int k = 0; k < 2; ++k) dst[n][k] = *(const PG8_LAS bf16x8*)(lds + PG8_SB(b, h) + boff + n * 2048 + k * 1024); } while (0)
; #define PG8_MMA(ai, bj, At, Bt) do { __builtin_amdgcn_s_setprio(1); _Pragma("unroll") for (int m = 0; m < 4; ++m) _Pragma("unroll") for (int n = 0; n < 2; ++n) _Pragma("unroll") for (int k = 0; k < 2; ++k) \
;         acc[ai][bj][m][n] = __builtin_amdgcn_mfma_f32_16x16x32_bf16(Bt[n][k], At[m][k], acc[ai][bj][m][n], 0, 0, 0); __builtin_amdgcn_s_setprio(0); } while (0)
; #define PG8_WAIT_V(n) asm volatile("s_waitcnt vmcnt(" #n ")" ::: "memory")
; #define PG8_WAIT_L(n) asm volatile("s_waitcnt lgkmcnt(" #n ")" ::: "memory")
; #define PG8_WAIT_V8_UNLESS(flag) asm volatile("s_cmp_lg_i32 %0, 0\n\ts_cbranch_scc1 .Lpg8rx%=\n\ts_waitcnt vmcnt(8)\n.Lpg8rx%=:" :: "s"(__builtin_amdgcn_readfirstlane(flag)) : "scc", "memory")
; #define PG8_BAR __builtin_amdgcn_s_barrier()
; #define PG8_SCHED __builtin_amdgcn_sched_barrier(0)
; template <class Epi, class Sched, bool ALIGN_EPI = false, bool SP2 = false>
; __device__ __forceinline__ void gemm_phase(PG8_LAS unsigned char* lds, const Gemm g, const Sched& S, const Epi& E) {
;     ...
;             PG8_WAIT_V8_UNLESS(rx); PG8_WAIT_L(0); PG8_BAR; PG8_MMA(1, 0, At, B0); PG8_MMA(1, 1, At, B1); PG8_BAR; PG8_SCHED;
;             PG8_STAGE(PG8_SA(0, 1), a2 + hstep, voffA); PG8_SCHED; PG8_LDB(B0, 1, 0); PG8_LDB(B1, 1, 1); PG8_SCHED; PG8_LDA(At, 1, 0);
;             PG8_WAIT_V(8); PG8_WAIT_L(0); PG8_BAR; PG8_MMA(0, 0, At, B0); PG8_MMA(0, 1, At, B1); PG8_BAR; PG8_SCHED;
.Lpg8rx1:
	s_waitcnt lgkmcnt(0)
	s_setprio 1
	s_barrier
	v_mfma_f32_16x16x32_bf16 v[60:63], v[144:147], v[178:181], v[60:63]
	v_mfma_f32_16x16x32_bf16 v[56:59], v[152:155], v[178:181], v[56:59]
	v_mfma_f32_16x16x32_bf16 v[44:47], v[144:147], v[186:189], v[44:47]
	v_mfma_f32_16x16x32_bf16 v[40:43], v[152:155], v[186:189], v[40:43]
	v_mfma_f32_16x16x32_bf16 v[28:31], v[144:147], v[208:211], v[28:31]
	v_mfma_f32_16x16x32_bf16 v[24:27], v[152:155], v[208:211], v[24:27]
	v_mfma_f32_16x16x32_bf16 v[12:15], v[144:147], v[216:219], v[12:15]
	v_mfma_f32_16x16x32_bf16 v[8:11], v[152:155], v[216:219], v[8:11]
	v_mfma_f32_16x16x32_bf16 v[60:63], v[148:151], v[182:185], v[60:63]
	v_mfma_f32_16x16x32_bf16 v[56:59], v[156:159], v[182:185], v[56:59]
	v_mfma_f32_16x16x32_bf16 v[44:47], v[148:151], v[204:207], v[44:47]
	v_mfma_f32_16x16x32_bf16 v[40:43], v[156:159], v[204:207], v[40:43]
	v_mfma_f32_16x16x32_bf16 v[28:31], v[148:151], v[212:215], v[28:31]
	v_mfma_f32_16x16x32_bf16 v[24:27], v[156:159], v[212:215], v[24:27]
	v_mfma_f32_16x16x32_bf16 v[12:15], v[148:151], v[220:223], v[12:15]
	v_mfma_f32_16x16x32_bf16 v[8:11], v[156:159], v[220:223], v[8:11]
	v_mfma_f32_16x16x32_bf16 v[52:55], v[160:163], v[178:181], v[52:55]
	v_mfma_f32_16x16x32_bf16 v[48:51], v[168:171], v[178:181], v[48:51]
	v_mfma_f32_16x16x32_bf16 v[36:39], v[160:163], v[186:189], v[36:39]
	v_mfma_f32_16x16x32_bf16 v[32:35], v[168:171], v[186:189], v[32:35]
	v_mfma_f32_16x16x32_bf16 v[20:23], v[160:163], v[208:211], v[20:23]
	v_mfma_f32_16x16x32_bf16 v[16:19], v[168:171], v[208:211], v[16:19]
	v_mfma_f32_16x16x32_bf16 v[4:7], v[160:163], v[216:219], v[4:7]
	v_mfma_f32_16x16x32_bf16 v[0:3], v[168:171], v[216:219], v[0:3]
	v_mfma_f32_16x16x32_bf16 v[52:55], v[164:167], v[182:185], v[52:55]
	v_mfma_f32_16x16x32_bf16 v[48:51], v[174:177], v[182:185], v[48:51]
	v_mfma_f32_16x16x32_bf16 v[36:39], v[164:167], v[204:207], v[36:39]
	v_mfma_f32_16x16x32_bf16 v[32:35], v[174:177], v[204:207], v[32:35]
	v_mfma_f32_16x16x32_bf16 v[20:23], v[164:167], v[212:215], v[20:23]
	v_mfma_f32_16x16x32_bf16 v[16:19], v[174:177], v[212:215], v[16:19]
	v_mfma_f32_16x16x32_bf16 v[4:7], v[164:167], v[220:223], v[4:7]
	v_mfma_f32_16x16x32_bf16 v[0:3], v[174:177], v[220:223], v[0:3]
	s_setprio 0
	s_barrier
	s_mov_b64 s[98:99], s[30:31]
	s_add_u32 s100, s30, 0x40000
	s_addc_u32 s101, s31, 0
	s_add_i32 s30, 0, 0x18000
	s_add_i32 s31, 0, 0x1c000
	v_add_u32_e32 v156, s30, v172
	v_add_u32_e32 v174, s31, v172
	ds_read_b128 v[144:147], v156
	ds_read_b128 v[148:151], v156 offset:1024
	ds_read_b128 v[152:155], v156 offset:2048
	ds_read_b128 v[156:159], v156 offset:3072
	ds_read_b128 v[160:163], v174
	ds_read_b128 v[164:167], v174 offset:1024
	ds_read_b128 v[168:171], v174 offset:2048
	ds_read_b128 v[174:177], v174 offset:3072
	ds_read_b128 v[178:181], v173 offset:32768
	ds_read_b128 v[182:185], v173 offset:33792
	ds_read_b128 v[186:189], v173 offset:34816
	ds_read_b128 v[204:207], v173 offset:35840
	ds_read_b128 v[208:211], v173 offset:36864
	ds_read_b128 v[212:215], v173 offset:37888
	s_mov_b32 m0, s52
	ds_read_b128 v[216:219], v173 offset:38912
	global_load_lds_dwordx4 v132, s[100:101]
	s_mov_b32 m0, s53
	ds_read_b128 v[220:223], v173 offset:39936
	global_load_lds_dwordx4 v136, s[100:101]
	s_waitcnt vmcnt(8)
	s_waitcnt lgkmcnt(0)
	s_setprio 1
	s_barrier
	v_mfma_f32_16x16x32_bf16 v[124:127], v[144:147], v[178:181], v[124:127]
	v_mfma_f32_16x16x32_bf16 v[120:123], v[152:155], v[178:181], v[120:123]
	v_mfma_f32_16x16x32_bf16 v[108:111], v[144:147], v[186:189], v[108:111]
	v_mfma_f32_16x16x32_bf16 v[104:107], v[152:155], v[186:189], v[104:107]
	v_mfma_f32_16x16x32_bf16 v[92:95], v[144:147], v[208:211], v[92:95]
	v_mfma_f32_16x16x32_bf16 v[88:91], v[152:155], v[208:211], v[88:91]
	v_mfma_f32_16x16x32_bf16 v[76:79], v[144:147], v[216:219], v[76:79]
	v_mfma_f32_16x16x32_bf16 v[72:75], v[152:155], v[216:219], v[72:75]
	v_mfma_f32_16x16x32_bf16 v[124:127], v[148:151], v[182:185], v[124:127]
	v_mfma_f32_16x16x32_bf16 v[120:123], v[156:159], v[182:185], v[120:123]
	v_mfma_f32_16x16x32_bf16 v[108:111], v[148:151], v[204:207], v[108:111]
	v_mfma_f32_16x16x32_bf16 v[104:107], v[156:159], v[204:207], v[104:107]
	v_mfma_f32_16x16x32_bf16 v[92:95], v[148:151], v[212:215], v[92:95]
	v_mfma_f32_16x16x32_bf16 v[88:91], v[156:159], v[212:215], v[88:91]
	v_mfma_f32_16x16x32_bf16 v[76:79], v[148:151], v[220:223], v[76:79]
	v_mfma_f32_16x16x32_bf16 v[72:75], v[156:159], v[220:223], v[72:75]
	v_mfma_f32_16x16x32_bf16 v[116:119], v[160:163], v[178:181], v[116:119]
	v_mfma_f32_16x16x32_bf16 v[112:115], v[168:171], v[178:181], v[112:115]
	v_mfma_f32_16x16x32_bf16 v[100:103], v[160:163], v[186:189], v[100:103]
	v_mfma_f32_16x16x32_bf16 v[96:99], v[168:171], v[186:189], v[96:99]
	v_mfma_f32_16x16x32_bf16 v[84:87], v[160:163], v[208:211], v[84:87]
	v_mfma_f32_16x16x32_bf16 v[80:83], v[168:171], v[208:211], v[80:83]
	v_mfma_f32_16x16x32_bf16 v[68:71], v[160:163], v[216:219], v[68:71]
	v_mfma_f32_16x16x32_bf16 v[64:67], v[168:171], v[216:219], v[64:67]
	v_mfma_f32_16x16x32_bf16 v[116:119], v[164:167], v[182:185], v[116:119]
	v_mfma_f32_16x16x32_bf16 v[112:115], v[174:177], v[182:185], v[112:115]
	v_mfma_f32_16x16x32_bf16 v[100:103], v[164:167], v[204:207], v[100:103]
	v_mfma_f32_16x16x32_bf16 v[96:99], v[174:177], v[204:207], v[96:99]
	v_mfma_f32_16x16x32_bf16 v[84:87], v[164:167], v[212:215], v[84:87]
	v_mfma_f32_16x16x32_bf16 v[80:83], v[174:177], v[212:215], v[80:83]
	v_mfma_f32_16x16x32_bf16 v[68:71], v[164:167], v[220:223], v[68:71]
	v_mfma_f32_16x16x32_bf16 v[64:67], v[174:177], v[220:223], v[64:67]
	s_setprio 0
	s_barrier
; #define PG8_STAGE(bufoff, gbase, voff) do { _Pragma("unroll") for (int _i = 0; _i < 2; ++_i) \
;         __builtin_amdgcn_global_load_lds((const unsigned*)((const char*)(gbase) + (voff)[_i]), (PG8_LAS unsigned*)(lds + (bufoff) + ldsw + _i * 8192), 16, 0, 0); } while (0)
; #define PG8_LDA(dst, b, h) do { _Pragma("unroll") for (int m = 0; m < 4; ++m) _Pragma("unroll") for (int k = 0; k < 2; ++k) dst[m][k] = *(const PG8_LAS bf16x8*)(lds + PG8_SA(b, h) + aoff + m * 2048 + k * 1024); } while (0)
; #define PG8_MMA(ai, bj, At, Bt) do { __builtin_amdgcn_s_setprio(1); _Pragma("unroll") for (int m = 0; m < 4; ++m) _Pragma("unroll") for (int n = 0; n < 2; ++n) _Pragma("unroll") for (int k = 0; k < 2; ++k) \
;         acc[ai][bj][m][n] = __builtin_amdgcn_mfma_f32_16x16x32_bf16(Bt[n][k], At[m][k], acc[ai][bj][m][n], 0, 0, 0); __builtin_amdgcn_s_setprio(0); } while (0)
; #define PG8_WAIT_V(n) asm volatile("s_waitcnt vmcnt(" #n ")" ::: "memory")
; #define PG8_WAIT_L(n) asm volatile("s_waitcnt lgkmcnt(" #n ")" ::: "memory")
; #define PG8_BAR __builtin_amdgcn_s_barrier()
; #define PG8_SCHED __builtin_amdgcn_sched_barrier(0)
; template <class Epi, class Sched, bool ALIGN_EPI = false, bool SP2 = false>
; __device__ __forceinline__ void gemm_phase(PG8_LAS unsigned char* lds, const Gemm g, const Sched& S, const Epi& E) {
;     ...
;             PG8_STAGE(PG8_SB(1, 0), b3, voffB); PG8_STAGE(PG8_SB(1, 1), b3 + hstep, voffB); PG8_STAGE(PG8_SA(1, 0), a3, voffA); PG8_SCHED; PG8_LDA(At, 1, 1);
;             PG8_WAIT_V(8); PG8_WAIT_L(0); PG8_BAR; PG8_MMA(1, 0, At, B0); PG8_MMA(1, 1, At, B1); PG8_BAR; PG8_SCHED;
;     ...
;         if constexpr (ALIGN_EPI) { if (wr == 0) PG8_BAR; }
	ds_read_b128 v[178:181], v173 offset:49152
	ds_read_b128 v[182:185], v173 offset:50176
	s_add_u32 s100, s28, 0x80
	s_addc_u32 s101, s29, 0
	s_add_u32 s28, s28, 0x40080
	s_addc_u32 s29, s29, 0
	s_add_u32 s98, s98, 0x80
	s_addc_u32 s99, s99, 0
	s_add_i32 m0, s30, s46
	ds_read_b128 v[186:189], v173 offset:51200
	global_load_lds_dwordx4 v134, s[100:101]
	s_add_i32 m0, m0, 0x2000
	ds_read_b128 v[204:207], v173 offset:52224
	global_load_lds_dwordx4 v138, s[100:101]
	s_add_i32 m0, s31, s46
	ds_read_b128 v[208:211], v173 offset:53248
	global_load_lds_dwordx4 v134, s[28:29]
	s_add_i32 m0, m0, 0x2000
	ds_read_b128 v[212:215], v173 offset:54272
	global_load_lds_dwordx4 v138, s[28:29]
	s_mov_b32 m0, s54
	ds_read_b128 v[216:219], v173 offset:55296
	global_load_lds_dwordx4 v132, s[98:99]
	s_mov_b32 m0, s55
	ds_read_b128 v[220:223], v173 offset:56320
	global_load_lds_dwordx4 v136, s[98:99]
	s_waitcnt vmcnt(8)
	s_waitcnt lgkmcnt(0)
	s_setprio 1
	s_barrier
	v_mfma_f32_16x16x32_bf16 v[60:63], v[144:147], v[178:181], v[60:63]
	v_mfma_f32_16x16x32_bf16 v[56:59], v[152:155], v[178:181], v[56:59]
	v_mfma_f32_16x16x32_bf16 v[44:47], v[144:147], v[186:189], v[44:47]
	v_mfma_f32_16x16x32_bf16 v[40:43], v[152:155], v[186:189], v[40:43]
	v_mfma_f32_16x16x32_bf16 v[28:31], v[144:147], v[208:211], v[28:31]
	v_mfma_f32_16x16x32_bf16 v[24:27], v[152:155], v[208:211], v[24:27]
	v_mfma_f32_16x16x32_bf16 v[12:15], v[144:147], v[216:219], v[12:15]
	v_mfma_f32_16x16x32_bf16 v[8:11], v[152:155], v[216:219], v[8:11]
	v_mfma_f32_16x16x32_bf16 v[60:63], v[148:151], v[182:185], v[60:63]
	v_mfma_f32_16x16x32_bf16 v[56:59], v[156:159], v[182:185], v[56:59]
	v_mfma_f32_16x16x32_bf16 v[44:47], v[148:151], v[204:207], v[44:47]
	v_mfma_f32_16x16x32_bf16 v[40:43], v[156:159], v[204:207], v[40:43]
	v_mfma_f32_16x16x32_bf16 v[28:31], v[148:151], v[212:215], v[28:31]
	v_mfma_f32_16x16x32_bf16 v[24:27], v[156:159], v[212:215], v[24:27]
	v_mfma_f32_16x16x32_bf16 v[12:15], v[148:151], v[220:223], v[12:15]
	v_mfma_f32_16x16x32_bf16 v[8:11], v[156:159], v[220:223], v[8:11]
	v_mfma_f32_16x16x32_bf16 v[52:55], v[160:163], v[178:181], v[52:55]
	v_mfma_f32_16x16x32_bf16 v[48:51], v[168:171], v[178:181], v[48:51]
	v_mfma_f32_16x16x32_bf16 v[36:39], v[160:163], v[186:189], v[36:39]
	v_mfma_f32_16x16x32_bf16 v[32:35], v[168:171], v[186:189], v[32:35]
	v_mfma_f32_16x16x32_bf16 v[20:23], v[160:163], v[208:211], v[20:23]
	v_mfma_f32_16x16x32_bf16 v[16:19], v[168:171], v[208:211], v[16:19]
	v_mfma_f32_16x16x32_bf16 v[4:7], v[160:163], v[216:219], v[4:7]
	v_mfma_f32_16x16x32_bf16 v[0:3], v[168:171], v[216:219], v[0:3]
	v_mfma_f32_16x16x32_bf16 v[52:55], v[164:167], v[182:185], v[52:55]
	v_mfma_f32_16x16x32_bf16 v[48:51], v[174:177], v[182:185], v[48:51]
	v_mfma_f32_16x16x32_bf16 v[36:39], v[164:167], v[204:207], v[36:39]
	v_mfma_f32_16x16x32_bf16 v[32:35], v[174:177], v[204:207], v[32:35]
	v_mfma_f32_16x16x32_bf16 v[20:23], v[164:167], v[212:215], v[20:23]
	v_mfma_f32_16x16x32_bf16 v[16:19], v[174:177], v[212:215], v[16:19]
	v_mfma_f32_16x16x32_bf16 v[4:7], v[164:167], v[220:223], v[4:7]
	v_mfma_f32_16x16x32_bf16 v[0:3], v[174:177], v[220:223], v[0:3]
	s_setprio 0
	s_barrier
	s_add_i32 s60, s60, 2
	s_add_u32 vcc_lo, vcc_lo, 0x100
	s_addc_u32 vcc_hi, vcc_hi, 0
	s_cmp_gt_u32 s60, 13
	s_cbranch_scc0 .LBB0_148
	s_and_b64 vcc, exec, s[62:63]
	s_cbranch_vccz .LBB0_151
	s_barrier

; #define PG8_STAGE(bufoff, gbase, voff) do { _Pragma("unroll") for (int _i = 0; _i < 2; ++_i) \
;         __builtin_amdgcn_global_load_lds((const unsigned*)((const char*)(gbase) + (voff)[_i]), (PG8_LAS unsigned*)(lds + (bufoff) + ldsw + _i * 8192), 16, 0, 0); } while (0)
; #define PG8_LDA(dst, b, h) do { _Pragma("unroll") for (int m = 0; m < 4; ++m) _Pragma("unroll") for (int k = 0; k < 2; ++k) dst[m][k] = *(const PG8_LAS bf16x8*)(lds + PG8_SA(b, h) + aoff + m * 2048 + k * 1024); } while (0)
; #define PG8_LDB(dst, b, h) do { _Pragma("unroll") for (int n = 0; n < 2; ++n) _Pragma("unroll") for (int k = 0; k < 2; ++k) dst[n][k] = *(const PG8_LAS bf16x8*)(lds + PG8_SB(b, h) + boff + n * 2048 + k * 1024); } while (0)
; #define PG8_MMA(ai, bj, At, Bt) do { __builtin_amdgcn_s_setprio(1); _Pragma("unroll") for (int m = 0; m < 4; ++m) _Pragma("unroll") for (int n = 0; n < 2; ++n) _Pragma("unroll") for (int k = 0; k < 2; ++k) \
;         acc[ai][bj][m][n] = __builtin_amdgcn_mfma_f32_16x16x32_bf16(Bt[n][k], At[m][k], acc[ai][bj][m][n], 0, 0, 0); __builtin_amdgcn_s_setprio(0); } while (0)
; #define PG8_WAIT_L(n) asm volatile("s_waitcnt lgkmcnt(" #n ")" ::: "memory")
; template <class Epi, class Sched, bool ALIGN_EPI = false, bool SP2 = false>
; __device__ __forceinline__ void gemm_phase(PG8_LAS unsigned char* lds, const Gemm g, const Sched& S, const Epi& E) {
;     ...
;             const bool last = (t == nt - 2);
;             const char* a1 = cA + (size_t)(t + 1) * kstep;
;             const char* a2 = last ? nA : cA + (size_t)(t + 2) * kstep; const char* b2 = last ? nB : cB + (size_t)(t + 2) * kstep;
;             const char* a3 = a2 + kstep; const char* b3 = b2 + kstep;
;             if (last && has_next) S.a_ready(nxt);
;             if constexpr (SP2) {
;             const int rx = (relax && t == 0) ? 1 : 0;
;             PG8_STAGE(PG8_SA(1, 1), a1 + hstep, voffA); PG8_SCHED; PG8_LDB(B0, 0, 0); PG8_LDB(B1, 0, 1); PG8_SCHED; PG8_LDA(At, 0, 0);
;             PG8_WAIT_V8_UNLESS(rx); PG8_WAIT_L(0); PG8_BAR; PG8_MMA(0, 0, At, B0); PG8_MMA(0, 1, At, B1); PG8_BAR; PG8_SCHED;
;             PG8_STAGE(PG8_SB(0, 0), b2, voffB); PG8_STAGE(PG8_SB(0, 1), b2 + hstep, voffB); PG8_STAGE(PG8_SA(0, 0), a2, voffA); PG8_SCHED; PG8_LDA(At, 0, 1);
;             PG8_WAIT_V8_UNLESS(rx); PG8_WAIT_L(0); PG8_BAR; PG8_MMA(1, 0, At, B0); PG8_MMA(1, 1, At, B1); PG8_BAR; PG8_SCHED;
.LBB0_514:
	s_add_u32 s28, s0, s62
	s_addc_u32 s29, s1, s63
	s_add_u32 s30, s28, 0x100
	s_addc_u32 s31, s29, 0
	s_add_u32 s98, s28, 0x40080
	s_addc_u32 s99, s29, 0
	s_add_u32 s59, s56, s62
	s_addc_u32 s65, s57, s63
	s_cmp_eq_u32 s62, 0
	s_cselect_b64 s[28:29], -1, 0
	s_and_b64 s[60:61], s[42:43], s[28:29]
	s_cmpk_eq_i32 s62, 0x700
	s_cselect_b32 s31, s19, s31
	s_cselect_b32 s30, s27, s30
	s_cselect_b32 s29, s17, s65
	s_cselect_b32 s28, s55, s59
	s_add_i32 s59, 0, 0x10000
	s_add_i32 s65, 0, 0x14000
	v_add_u32_e32 v136, s59, v247
	v_add_u32_e32 v160, s65, v247
	ds_read_b128 v[120:123], v136
	ds_read_b128 v[128:131], v136 offset:1024
	ds_read_b128 v[132:135], v136 offset:2048
	ds_read_b128 v[136:139], v136 offset:3072
	ds_read_b128 v[140:143], v160
	ds_read_b128 v[144:147], v160 offset:1024
	ds_read_b128 v[156:159], v160 offset:2048
	ds_read_b128 v[160:163], v160 offset:3072
	ds_read_b128 v[164:167], v248
	ds_read_b128 v[168:171], v248 offset:1024
	ds_read_b128 v[172:175], v248 offset:2048
	ds_read_b128 v[176:179], v248 offset:3072
	ds_read_b128 v[180:183], v248 offset:4096
	ds_read_b128 v[184:187], v248 offset:5120
	ds_read_b128 v[188:191], v248 offset:6144
	s_add_i32 m0, s41, 0xc000
	s_and_b32 s66, s60, 1
	global_load_lds_dwordx4 v204, s[98:99]
	s_add_i32 m0, s41, 0xe000
	ds_read_b128 v[214:217], v248 offset:7168
	global_load_lds_dwordx4 v206, s[98:99]
	s_cmp_lg_i32 s66, 0
	s_cbranch_scc1 .Lpg8rx2
	s_waitcnt vmcnt(8)
.Lpg8rx2:
	s_waitcnt lgkmcnt(0)
	s_setprio 1
	s_barrier
	v_mfma_f32_16x16x32_bf16 v[152:155], v[120:123], v[164:167], v[152:155]
	v_mfma_f32_16x16x32_bf16 v[148:151], v[132:135], v[164:167], v[148:151]
	v_mfma_f32_16x16x32_bf16 v[108:111], v[120:123], v[172:175], v[108:111]
	v_mfma_f32_16x16x32_bf16 v[104:107], v[132:135], v[172:175], v[104:107]
	v_mfma_f32_16x16x32_bf16 v[92:95], v[120:123], v[180:183], v[92:95]
	v_mfma_f32_16x16x32_bf16 v[88:91], v[132:135], v[180:183], v[88:91]
	v_mfma_f32_16x16x32_bf16 v[76:79], v[120:123], v[188:191], v[76:79]
	v_mfma_f32_16x16x32_bf16 v[72:75], v[132:135], v[188:191], v[72:75]
	v_mfma_f32_16x16x32_bf16 v[152:155], v[128:131], v[168:171], v[152:155]
	v_mfma_f32_16x16x32_bf16 v[148:151], v[136:139], v[168:171], v[148:151]
	v_mfma_f32_16x16x32_bf16 v[108:111], v[128:131], v[176:179], v[108:111]
	v_mfma_f32_16x16x32_bf16 v[104:107], v[136:139], v[176:179], v[104:107]
	v_mfma_f32_16x16x32_bf16 v[92:95], v[128:131], v[184:187], v[92:95]
	v_mfma_f32_16x16x32_bf16 v[88:91], v[136:139], v[184:187], v[88:91]
	v_mfma_f32_16x16x32_bf16 v[76:79], v[128:131], v[214:217], v[76:79]
	v_mfma_f32_16x16x32_bf16 v[72:75], v[136:139], v[214:217], v[72:75]
	v_mfma_f32_16x16x32_bf16 v[124:127], v[140:143], v[164:167], v[124:127]
	v_mfma_f32_16x16x32_bf16 v[112:115], v[156:159], v[164:167], v[112:115]
	v_mfma_f32_16x16x32_bf16 v[100:103], v[140:143], v[172:175], v[100:103]
	v_mfma_f32_16x16x32_bf16 v[96:99], v[156:159], v[172:175], v[96:99]
	v_mfma_f32_16x16x32_bf16 v[84:87], v[140:143], v[180:183], v[84:87]
	v_mfma_f32_16x16x32_bf16 v[80:83], v[156:159], v[180:183], v[80:83]
	v_mfma_f32_16x16x32_bf16 v[68:71], v[140:143], v[188:191], v[68:71]
	v_mfma_f32_16x16x32_bf16 v[64:67], v[156:159], v[188:191], v[64:67]
	v_mfma_f32_16x16x32_bf16 v[124:127], v[144:147], v[168:171], v[124:127]
	v_mfma_f32_16x16x32_bf16 v[112:115], v[160:163], v[168:171], v[112:115]
	v_mfma_f32_16x16x32_bf16 v[100:103], v[144:147], v[176:179], v[100:103]
	v_mfma_f32_16x16x32_bf16 v[96:99], v[160:163], v[176:179], v[96:99]
	v_mfma_f32_16x16x32_bf16 v[84:87], v[144:147], v[184:187], v[84:87]
	v_mfma_f32_16x16x32_bf16 v[80:83], v[160:163], v[184:187], v[80:83]
	v_mfma_f32_16x16x32_bf16 v[68:71], v[144:147], v[214:217], v[68:71]
	v_mfma_f32_16x16x32_bf16 v[64:67], v[160:163], v[214:217], v[64:67]
	s_setprio 0
	s_barrier
	ds_read_b128 v[164:167], v248 offset:16384
	ds_read_b128 v[168:171], v248 offset:17408
	s_add_u32 s60, s28, 0x40000
	s_addc_u32 s61, s29, 0
	s_add_i32 m0, s59, s39
	ds_read_b128 v[172:175], v248 offset:18432
	global_load_lds_dwordx4 v194, s[28:29]
	s_add_i32 m0, m0, 0x2000
	ds_read_b128 v[176:179], v248 offset:19456
	global_load_lds_dwordx4 v208, s[28:29]
	s_add_i32 m0, s65, s39
	ds_read_b128 v[180:183], v248 offset:20480
	global_load_lds_dwordx4 v194, s[60:61]
	s_add_i32 m0, m0, 0x2000
	ds_read_b128 v[184:187], v248 offset:21504
	global_load_lds_dwordx4 v208, s[60:61]
	s_mov_b32 m0, s41
	ds_read_b128 v[188:191], v248 offset:22528
	global_load_lds_dwordx4 v204, s[30:31]
	s_mov_b32 m0, s44
	ds_read_b128 v[214:217], v248 offset:23552
	global_load_lds_dwordx4 v206, s[30:31]
	s_cmp_lg_i32 s66, 0
	s_cbranch_scc1 .Lpg8rx3
	s_waitcnt vmcnt(8)
; #define PG8_STAGE(bufoff, gbase, voff) do { _Pragma("unroll") for (int _i = 0; _i < 2; ++_i) \
;         __builtin_amdgcn_global_load_lds((const unsigned*)((const char*)(gbase) + (voff)[_i]), (PG8_LAS unsigned*)(lds + (bufoff) + ldsw + _i * 8192), 16, 0, 0); } while (0)
; #define PG8_LDA(dst, b, h) do { _Pragma("unroll") for (int m = 0; m < 4; ++m) _Pragma("unroll") for (int k = 0; k < 2; ++k) dst[m][k] = *(const PG8_LAS bf16x8*)(lds + PG8_SA(b, h) + aoff + m * 2048 + k * 1024); } while (0)
; #define PG8_LDB(dst, b, h) do { _Pragma("unroll") for (int n = 0; n < 2; ++n) _Pragma("unroll") for (int k = 0; k < 2; ++k) dst[n][k] = *(const PG8_LAS bf16x8*)(lds + PG8_SB(b, h) + boff + n * 2048 + k * 1024); } while (0)
; #define PG8_MMA(ai, bj, At, Bt) do { __builtin_amdgcn_s_setprio(1); _Pragma("unroll") for (int m = 0; m < 4; ++m) _Pragma("unroll") for (int n = 0; n < 2; ++n) _Pragma("unroll") for (int k = 0; k < 2; ++k) \
;         acc[ai][bj][m][n] = __builtin_amdgcn_mfma_f32_16x16x32_bf16(Bt[n][k], At[m][k], acc[ai][bj][m][n], 0, 0, 0); __builtin_amdgcn_s_setprio(0); } while (0)
; #define PG8_WAIT_V(n) asm volatile("s_waitcnt vmcnt(" #n ")" ::: "memory")
; #define PG8_WAIT_L(n) asm volatile("s_waitcnt lgkmcnt(" #n ")" ::: "memory")
; #define PG8_WAIT_V8_UNLESS(flag) asm volatile("s_cmp_lg_i32 %0, 0\n\ts_cbranch_scc1 .Lpg8rx%=\n\ts_waitcnt vmcnt(8)\n.Lpg8rx%=:" :: "s"(__builtin_amdgcn_readfirstlane(flag)) : "scc", "memory")
; #define PG8_BAR __builtin_amdgcn_s_barrier()
; #define PG8_SCHED __builtin_amdgcn_sched_barrier(0)
; template <class Epi, class Sched, bool ALIGN_EPI = false, bool SP2 = false>
; __device__ __forceinline__ void gemm_phase(PG8_LAS unsigned char* lds, const Gemm g, const Sched& S, const Epi& E) {
;     ...
;             PG8_WAIT_V8_UNLESS(rx); PG8_WAIT_L(0); PG8_BAR; PG8_MMA(1, 0, At, B0); PG8_MMA(1, 1, At, B1); PG8_BAR; PG8_SCHED;
;             PG8_STAGE(PG8_SA(0, 1), a2 + hstep, voffA); PG8_SCHED; PG8_LDB(B0, 1, 0); PG8_LDB(B1, 1, 1); PG8_SCHED; PG8_LDA(At, 1, 0);
;             PG8_WAIT_V(8); PG8_WAIT_L(0); PG8_BAR; PG8_MMA(0, 0, At, B0); PG8_MMA(0, 1, At, B1); PG8_BAR; PG8_SCHED;
.Lpg8rx3:
	s_waitcnt lgkmcnt(0)
	s_setprio 1
	s_barrier
	v_mfma_f32_16x16x32_bf16 v[60:63], v[120:123], v[164:167], v[60:63]
	v_mfma_f32_16x16x32_bf16 v[56:59], v[132:135], v[164:167], v[56:59]
	v_mfma_f32_16x16x32_bf16 v[44:47], v[120:123], v[172:175], v[44:47]
	v_mfma_f32_16x16x32_bf16 v[40:43], v[132:135], v[172:175], v[40:43]
	v_mfma_f32_16x16x32_bf16 v[28:31], v[120:123], v[180:183], v[28:31]
	v_mfma_f32_16x16x32_bf16 v[24:27], v[132:135], v[180:183], v[24:27]
	v_mfma_f32_16x16x32_bf16 v[12:15], v[120:123], v[188:191], v[12:15]
	v_mfma_f32_16x16x32_bf16 v[8:11], v[132:135], v[188:191], v[8:11]
	v_mfma_f32_16x16x32_bf16 v[60:63], v[128:131], v[168:171], v[60:63]
	v_mfma_f32_16x16x32_bf16 v[56:59], v[136:139], v[168:171], v[56:59]
	v_mfma_f32_16x16x32_bf16 v[44:47], v[128:131], v[176:179], v[44:47]
	v_mfma_f32_16x16x32_bf16 v[40:43], v[136:139], v[176:179], v[40:43]
	v_mfma_f32_16x16x32_bf16 v[28:31], v[128:131], v[184:187], v[28:31]
	v_mfma_f32_16x16x32_bf16 v[24:27], v[136:139], v[184:187], v[24:27]
	v_mfma_f32_16x16x32_bf16 v[12:15], v[128:131], v[214:217], v[12:15]
	v_mfma_f32_16x16x32_bf16 v[8:11], v[136:139], v[214:217], v[8:11]
	v_mfma_f32_16x16x32_bf16 v[52:55], v[140:143], v[164:167], v[52:55]
	v_mfma_f32_16x16x32_bf16 v[48:51], v[156:159], v[164:167], v[48:51]
	v_mfma_f32_16x16x32_bf16 v[36:39], v[140:143], v[172:175], v[36:39]
	v_mfma_f32_16x16x32_bf16 v[32:35], v[156:159], v[172:175], v[32:35]
	v_mfma_f32_16x16x32_bf16 v[20:23], v[140:143], v[180:183], v[20:23]
	v_mfma_f32_16x16x32_bf16 v[16:19], v[156:159], v[180:183], v[16:19]
	v_mfma_f32_16x16x32_bf16 v[4:7], v[140:143], v[188:191], v[4:7]
	v_mfma_f32_16x16x32_bf16 v[0:3], v[156:159], v[188:191], v[0:3]
	v_mfma_f32_16x16x32_bf16 v[52:55], v[144:147], v[168:171], v[52:55]
	v_mfma_f32_16x16x32_bf16 v[48:51], v[160:163], v[168:171], v[48:51]
	v_mfma_f32_16x16x32_bf16 v[36:39], v[144:147], v[176:179], v[36:39]
	v_mfma_f32_16x16x32_bf16 v[32:35], v[160:163], v[176:179], v[32:35]
	v_mfma_f32_16x16x32_bf16 v[20:23], v[144:147], v[184:187], v[20:23]
	v_mfma_f32_16x16x32_bf16 v[16:19], v[160:163], v[184:187], v[16:19]
	v_mfma_f32_16x16x32_bf16 v[4:7], v[144:147], v[214:217], v[4:7]
	v_mfma_f32_16x16x32_bf16 v[0:3], v[160:163], v[214:217], v[0:3]
	s_setprio 0
	s_barrier
	s_mov_b64 s[98:99], s[30:31]
	s_add_u32 s100, s30, 0x40000
	s_addc_u32 s101, s31, 0
	s_add_i32 s30, 0, 0x18000
	s_add_i32 s31, 0, 0x1c000
	v_add_u32_e32 v136, s30, v247
	v_add_u32_e32 v160, s31, v247
	ds_read_b128 v[120:123], v136
	ds_read_b128 v[128:131], v136 offset:1024
	ds_read_b128 v[132:135], v136 offset:2048
	ds_read_b128 v[136:139], v136 offset:3072
	ds_read_b128 v[140:143], v160
	ds_read_b128 v[144:147], v160 offset:1024
	ds_read_b128 v[156:159], v160 offset:2048
	ds_read_b128 v[160:163], v160 offset:3072
	ds_read_b128 v[164:167], v248 offset:32768
	ds_read_b128 v[168:171], v248 offset:33792
	ds_read_b128 v[172:175], v248 offset:34816
	ds_read_b128 v[176:179], v248 offset:35840
	ds_read_b128 v[180:183], v248 offset:36864
	ds_read_b128 v[184:187], v248 offset:37888
	s_mov_b32 m0, s46
	ds_read_b128 v[188:191], v248 offset:38912
	global_load_lds_dwordx4 v204, s[100:101]
	s_mov_b32 m0, s48
	ds_read_b128 v[214:217], v248 offset:39936
	global_load_lds_dwordx4 v206, s[100:101]
	s_waitcnt vmcnt(8)
	s_waitcnt lgkmcnt(0)
	s_setprio 1
	s_barrier
	v_mfma_f32_16x16x32_bf16 v[152:155], v[120:123], v[164:167], v[152:155]
	v_mfma_f32_16x16x32_bf16 v[148:151], v[132:135], v[164:167], v[148:151]
	v_mfma_f32_16x16x32_bf16 v[108:111], v[120:123], v[172:175], v[108:111]
	v_mfma_f32_16x16x32_bf16 v[104:107], v[132:135], v[172:175], v[104:107]
	v_mfma_f32_16x16x32_bf16 v[92:95], v[120:123], v[180:183], v[92:95]
	v_mfma_f32_16x16x32_bf16 v[88:91], v[132:135], v[180:183], v[88:91]
	v_mfma_f32_16x16x32_bf16 v[76:79], v[120:123], v[188:191], v[76:79]
	v_mfma_f32_16x16x32_bf16 v[72:75], v[132:135], v[188:191], v[72:75]
	v_mfma_f32_16x16x32_bf16 v[152:155], v[128:131], v[168:171], v[152:155]
	v_mfma_f32_16x16x32_bf16 v[148:151], v[136:139], v[168:171], v[148:151]
	v_mfma_f32_16x16x32_bf16 v[108:111], v[128:131], v[176:179], v[108:111]
	v_mfma_f32_16x16x32_bf16 v[104:107], v[136:139], v[176:179], v[104:107]
	v_mfma_f32_16x16x32_bf16 v[92:95], v[128:131], v[184:187], v[92:95]
	v_mfma_f32_16x16x32_bf16 v[88:91], v[136:139], v[184:187], v[88:91]
	v_mfma_f32_16x16x32_bf16 v[76:79], v[128:131], v[214:217], v[76:79]
	v_mfma_f32_16x16x32_bf16 v[72:75], v[136:139], v[214:217], v[72:75]
	v_mfma_f32_16x16x32_bf16 v[124:127], v[140:143], v[164:167], v[124:127]
	v_mfma_f32_16x16x32_bf16 v[112:115], v[156:159], v[164:167], v[112:115]
	v_mfma_f32_16x16x32_bf16 v[100:103], v[140:143], v[172:175], v[100:103]
	v_mfma_f32_16x16x32_bf16 v[96:99], v[156:159], v[172:175], v[96:99]
	v_mfma_f32_16x16x32_bf16 v[84:87], v[140:143], v[180:183], v[84:87]
	v_mfma_f32_16x16x32_bf16 v[80:83], v[156:159], v[180:183], v[80:83]
	v_mfma_f32_16x16x32_bf16 v[68:71], v[140:143], v[188:191], v[68:71]
	v_mfma_f32_16x16x32_bf16 v[64:67], v[156:159], v[188:191], v[64:67]
	v_mfma_f32_16x16x32_bf16 v[124:127], v[144:147], v[168:171], v[124:127]
	v_mfma_f32_16x16x32_bf16 v[112:115], v[160:163], v[168:171], v[112:115]
	v_mfma_f32_16x16x32_bf16 v[100:103], v[144:147], v[176:179], v[100:103]
	v_mfma_f32_16x16x32_bf16 v[96:99], v[160:163], v[176:179], v[96:99]
	v_mfma_f32_16x16x32_bf16 v[84:87], v[144:147], v[184:187], v[84:87]
	v_mfma_f32_16x16x32_bf16 v[80:83], v[160:163], v[184:187], v[80:83]
	v_mfma_f32_16x16x32_bf16 v[68:71], v[144:147], v[214:217], v[68:71]
	v_mfma_f32_16x16x32_bf16 v[64:67], v[160:163], v[214:217], v[64:67]
	s_setprio 0
	s_barrier
; #define PG8_STAGE(bufoff, gbase, voff) do { _Pragma("unroll") for (int _i = 0; _i < 2; ++_i) \
;         __builtin_amdgcn_global_load_lds((const unsigned*)((const char*)(gbase) + (voff)[_i]), (PG8_LAS unsigned*)(lds + (bufoff) + ldsw + _i * 8192), 16, 0, 0); } while (0)
; #define PG8_LDA(dst, b, h) do { _Pragma("unroll") for (int m = 0; m < 4; ++m) _Pragma("unroll") for (int k = 0; k < 2; ++k) dst[m][k] = *(const PG8_LAS bf16x8*)(lds + PG8_SA(b, h) + aoff + m * 2048 + k * 1024); } while (0)
; #define PG8_MMA(ai, bj, At, Bt) do { __builtin_amdgcn_s_setprio(1); _Pragma("unroll") for (int m = 0; m < 4; ++m) _Pragma("unroll") for (int n = 0; n < 2; ++n) _Pragma("unroll") for (int k = 0; k < 2; ++k) \
;         acc[ai][bj][m][n] = __builtin_amdgcn_mfma_f32_16x16x32_bf16(Bt[n][k], At[m][k], acc[ai][bj][m][n], 0, 0, 0); __builtin_amdgcn_s_setprio(0); } while (0)
; #define PG8_WAIT_V(n) asm volatile("s_waitcnt vmcnt(" #n ")" ::: "memory")
; #define PG8_WAIT_L(n) asm volatile("s_waitcnt lgkmcnt(" #n ")" ::: "memory")
; #define PG8_BAR __builtin_amdgcn_s_barrier()
; #define PG8_SCHED __builtin_amdgcn_sched_barrier(0)
; template <class Epi, class Sched, bool ALIGN_EPI = false, bool SP2 = false>
; __device__ __forceinline__ void gemm_phase(PG8_LAS unsigned char* lds, const Gemm g, const Sched& S, const Epi& E) {
;     ...
;             PG8_STAGE(PG8_SB(1, 0), b3, voffB); PG8_STAGE(PG8_SB(1, 1), b3 + hstep, voffB); PG8_STAGE(PG8_SA(1, 0), a3, voffA); PG8_SCHED; PG8_LDA(At, 1, 1);
;             PG8_WAIT_V(8); PG8_WAIT_L(0); PG8_BAR; PG8_MMA(1, 0, At, B0); PG8_MMA(1, 1, At, B1); PG8_BAR; PG8_SCHED;
;     ...
;         if constexpr (ALIGN_EPI) { if (wr == 0) PG8_BAR; }
	ds_read_b128 v[164:167], v248 offset:49152
	ds_read_b128 v[168:171], v248 offset:50176
	s_add_u32 s100, s28, 0x80
	s_addc_u32 s101, s29, 0
	s_add_u32 s28, s28, 0x40080
	s_addc_u32 s29, s29, 0
	s_add_u32 s98, s98, 0x80
	s_addc_u32 s99, s99, 0
	s_add_i32 m0, s30, s39
	ds_read_b128 v[172:175], v248 offset:51200
	global_load_lds_dwordx4 v194, s[100:101]
	s_add_i32 m0, m0, 0x2000
	ds_read_b128 v[176:179], v248 offset:52224
	global_load_lds_dwordx4 v208, s[100:101]
	s_add_i32 m0, s31, s39
	ds_read_b128 v[180:183], v248 offset:53248
	global_load_lds_dwordx4 v194, s[28:29]
	s_add_i32 m0, m0, 0x2000
	ds_read_b128 v[184:187], v248 offset:54272
	global_load_lds_dwordx4 v208, s[28:29]
	s_mov_b32 m0, s50
	ds_read_b128 v[188:191], v248 offset:55296
	global_load_lds_dwordx4 v204, s[98:99]
	s_mov_b32 m0, s51
	ds_read_b128 v[214:217], v248 offset:56320
	global_load_lds_dwordx4 v206, s[98:99]
	s_waitcnt vmcnt(8)
	s_waitcnt lgkmcnt(0)
	s_setprio 1
	s_barrier
	v_mfma_f32_16x16x32_bf16 v[60:63], v[120:123], v[164:167], v[60:63]
	v_mfma_f32_16x16x32_bf16 v[56:59], v[132:135], v[164:167], v[56:59]
	v_mfma_f32_16x16x32_bf16 v[44:47], v[120:123], v[172:175], v[44:47]
	v_mfma_f32_16x16x32_bf16 v[40:43], v[132:135], v[172:175], v[40:43]
	v_mfma_f32_16x16x32_bf16 v[28:31], v[120:123], v[180:183], v[28:31]
	v_mfma_f32_16x16x32_bf16 v[24:27], v[132:135], v[180:183], v[24:27]
	v_mfma_f32_16x16x32_bf16 v[12:15], v[120:123], v[188:191], v[12:15]
	v_mfma_f32_16x16x32_bf16 v[8:11], v[132:135], v[188:191], v[8:11]
	v_mfma_f32_16x16x32_bf16 v[60:63], v[128:131], v[168:171], v[60:63]
	v_mfma_f32_16x16x32_bf16 v[56:59], v[136:139], v[168:171], v[56:59]
	v_mfma_f32_16x16x32_bf16 v[44:47], v[128:131], v[176:179], v[44:47]
	v_mfma_f32_16x16x32_bf16 v[40:43], v[136:139], v[176:179], v[40:43]
	v_mfma_f32_16x16x32_bf16 v[28:31], v[128:131], v[184:187], v[28:31]
	v_mfma_f32_16x16x32_bf16 v[24:27], v[136:139], v[184:187], v[24:27]
	v_mfma_f32_16x16x32_bf16 v[12:15], v[128:131], v[214:217], v[12:15]
	v_mfma_f32_16x16x32_bf16 v[8:11], v[136:139], v[214:217], v[8:11]
	v_mfma_f32_16x16x32_bf16 v[52:55], v[140:143], v[164:167], v[52:55]
	v_mfma_f32_16x16x32_bf16 v[48:51], v[156:159], v[164:167], v[48:51]
	v_mfma_f32_16x16x32_bf16 v[36:39], v[140:143], v[172:175], v[36:39]
	v_mfma_f32_16x16x32_bf16 v[32:35], v[156:159], v[172:175], v[32:35]
	v_mfma_f32_16x16x32_bf16 v[20:23], v[140:143], v[180:183], v[20:23]
	v_mfma_f32_16x16x32_bf16 v[16:19], v[156:159], v[180:183], v[16:19]
	v_mfma_f32_16x16x32_bf16 v[4:7], v[140:143], v[188:191], v[4:7]
	v_mfma_f32_16x16x32_bf16 v[0:3], v[156:159], v[188:191], v[0:3]
	v_mfma_f32_16x16x32_bf16 v[52:55], v[144:147], v[168:171], v[52:55]
	v_mfma_f32_16x16x32_bf16 v[48:51], v[160:163], v[168:171], v[48:51]
	v_mfma_f32_16x16x32_bf16 v[36:39], v[144:147], v[176:179], v[36:39]
	v_mfma_f32_16x16x32_bf16 v[32:35], v[160:163], v[176:179], v[32:35]
	v_mfma_f32_16x16x32_bf16 v[20:23], v[144:147], v[184:187], v[20:23]
	v_mfma_f32_16x16x32_bf16 v[16:19], v[160:163], v[184:187], v[16:19]
	v_mfma_f32_16x16x32_bf16 v[4:7], v[144:147], v[214:217], v[4:7]
	v_mfma_f32_16x16x32_bf16 v[0:3], v[160:163], v[214:217], v[0:3]
	s_setprio 0
	s_barrier
	s_add_i32 s58, s58, 2
	s_add_u32 s62, s62, 0x100
	s_addc_u32 s63, s63, 0
	s_cmp_gt_u32 s58, 13
	s_cbranch_scc0 .LBB0_514
	s_and_b64 vcc, exec, s[14:15]
	s_cbranch_vccz .LBB0_517
	s_barrier

; #define PG8_STAGE(bufoff, gbase, voff) do { _Pragma("unroll") for (int _i = 0; _i < 2; ++_i) \
;         __builtin_amdgcn_global_load_lds((const unsigned*)((const char*)(gbase) + (voff)[_i]), (PG8_LAS unsigned*)(lds + (bufoff) + ldsw + _i * 8192), 16, 0, 0); } while (0)
; #define PG8_LDA(dst, b, h) do { _Pragma("unroll") for (int m = 0; m < 4; ++m) _Pragma("unroll") for (int k = 0; k < 2; ++k) dst[m][k] = *(const PG8_LAS bf16x8*)(lds + PG8_SA(b, h) + aoff + m * 2048 + k * 1024); } while (0)
; #define PG8_LDB(dst, b, h) do { _Pragma("unroll") for (int n = 0; n < 2; ++n) _Pragma("unroll") for (int k = 0; k < 2; ++k) dst[n][k] = *(const PG8_LAS bf16x8*)(lds + PG8_SB(b, h) + boff + n * 2048 + k * 1024); } while (0)
; #define PG8_MMA(ai, bj, At, Bt) do { __builtin_amdgcn_s_setprio(1); _Pragma("unroll") for (int m = 0; m < 4; ++m) _Pragma("unroll") for (int n = 0; n < 2; ++n) _Pragma("unroll") for (int k = 0; k < 2; ++k) \
;         acc[ai][bj][m][n] = __builtin_amdgcn_mfma_f32_16x16x32_bf16(Bt[n][k], At[m][k], acc[ai][bj][m][n], 0, 0, 0); __builtin_amdgcn_s_setprio(0); } while (0)
; #define PG8_WAIT_L(n) asm volatile("s_waitcnt lgkmcnt(" #n ")" ::: "memory")
; template <class Epi, class Sched, bool ALIGN_EPI = false, bool SP2 = false>
; __device__ __forceinline__ void gemm_phase(PG8_LAS unsigned char* lds, const Gemm g, const Sched& S, const Epi& E) {
;     ...
;             const bool last = (t == nt - 2);
;             const char* a1 = cA + (size_t)(t + 1) * kstep;
;             const char* a2 = last ? nA : cA + (size_t)(t + 2) * kstep; const char* b2 = last ? nB : cB + (size_t)(t + 2) * kstep;
;             const char* a3 = a2 + kstep; const char* b3 = b2 + kstep;
;             if (last && has_next) S.a_ready(nxt);
;             if constexpr (SP2) {
;             const int rx = (relax && t == 0) ? 1 : 0;
;             PG8_STAGE(PG8_SA(1, 1), a1 + hstep, voffA); PG8_SCHED; PG8_LDB(B0, 0, 0); PG8_LDB(B1, 0, 1); PG8_SCHED; PG8_LDA(At, 0, 0);
;             PG8_WAIT_V8_UNLESS(rx); PG8_WAIT_L(0); PG8_BAR; PG8_MMA(0, 0, At, B0); PG8_MMA(0, 1, At, B1); PG8_BAR; PG8_SCHED;
;             PG8_STAGE(PG8_SB(0, 0), b2, voffB); PG8_STAGE(PG8_SB(0, 1), b2 + hstep, voffB); PG8_STAGE(PG8_SA(0, 0), a2, voffA); PG8_SCHED; PG8_LDA(At, 0, 1);
;             PG8_WAIT_V8_UNLESS(rx); PG8_WAIT_L(0); PG8_BAR; PG8_MMA(1, 0, At, B0); PG8_MMA(1, 1, At, B1); PG8_BAR; PG8_SCHED;
.LBB0_611:
	s_add_u32 s28, s24, s40
	s_addc_u32 s29, s25, s41
	s_add_u32 s30, s28, 0x100
	s_addc_u32 s31, s29, 0
	s_add_u32 s98, s28, 0x40080
	s_addc_u32 s99, s29, 0
	s_add_u32 s59, s56, s40
	s_addc_u32 s62, s57, s41
	s_cmp_eq_u32 s40, 0
	s_cselect_b64 s[28:29], -1, 0
	s_and_b64 s[60:61], s[26:27], s[28:29]
	s_cmpk_eq_i32 s40, 0x700
	s_cselect_b32 s31, s13, s31
	s_cselect_b32 s30, s54, s30
	s_cselect_b32 s29, s11, s62
	s_cselect_b32 s28, s55, s59
	s_add_i32 s59, 0, 0x10000
	s_add_i32 s62, 0, 0x14000
	v_add_u32_e32 v144, s59, v183
	v_add_u32_e32 v172, s62, v183
	ds_read_b128 v[132:135], v144
	ds_read_b128 v[136:139], v144 offset:1024
	ds_read_b128 v[140:143], v144 offset:2048
	ds_read_b128 v[144:147], v144 offset:3072
	ds_read_b128 v[148:151], v172
	ds_read_b128 v[164:167], v172 offset:1024
	ds_read_b128 v[168:171], v172 offset:2048
	ds_read_b128 v[172:175], v172 offset:3072
	ds_read_b128 v[176:179], v185
	ds_read_b128 v[186:189], v185 offset:1024
	ds_read_b128 v[204:207], v185 offset:2048
	ds_read_b128 v[208:211], v185 offset:3072
	ds_read_b128 v[212:215], v185 offset:4096
	ds_read_b128 v[216:219], v185 offset:5120
	ds_read_b128 v[220:223], v185 offset:6144
	s_add_i32 m0, s21, 0xc000
	s_and_b32 s63, s60, 1
	global_load_lds_dwordx4 v152, s[98:99]
	s_add_i32 m0, s21, 0xe000
	ds_read_b128 v[224:227], v185 offset:7168
	global_load_lds_dwordx4 v156, s[98:99]
	s_cmp_lg_i32 s63, 0
	s_cbranch_scc1 .Lpg8rx4
	s_waitcnt vmcnt(8)
.Lpg8rx4:
	s_waitcnt lgkmcnt(0)
	s_setprio 1
	s_barrier
	v_mfma_f32_16x16x32_bf16 v[124:127], v[132:135], v[176:179], v[124:127]
	v_mfma_f32_16x16x32_bf16 v[120:123], v[140:143], v[176:179], v[120:123]
	v_mfma_f32_16x16x32_bf16 v[108:111], v[132:135], v[204:207], v[108:111]
	v_mfma_f32_16x16x32_bf16 v[104:107], v[140:143], v[204:207], v[104:107]
	v_mfma_f32_16x16x32_bf16 v[92:95], v[132:135], v[212:215], v[92:95]
	v_mfma_f32_16x16x32_bf16 v[88:91], v[140:143], v[212:215], v[88:91]
	v_mfma_f32_16x16x32_bf16 v[76:79], v[132:135], v[220:223], v[76:79]
	v_mfma_f32_16x16x32_bf16 v[72:75], v[140:143], v[220:223], v[72:75]
	v_mfma_f32_16x16x32_bf16 v[124:127], v[136:139], v[186:189], v[124:127]
	v_mfma_f32_16x16x32_bf16 v[120:123], v[144:147], v[186:189], v[120:123]
	v_mfma_f32_16x16x32_bf16 v[108:111], v[136:139], v[208:211], v[108:111]
	v_mfma_f32_16x16x32_bf16 v[104:107], v[144:147], v[208:211], v[104:107]
	v_mfma_f32_16x16x32_bf16 v[92:95], v[136:139], v[216:219], v[92:95]
	v_mfma_f32_16x16x32_bf16 v[88:91], v[144:147], v[216:219], v[88:91]
	v_mfma_f32_16x16x32_bf16 v[76:79], v[136:139], v[224:227], v[76:79]
	v_mfma_f32_16x16x32_bf16 v[72:75], v[144:147], v[224:227], v[72:75]
	v_mfma_f32_16x16x32_bf16 v[116:119], v[148:151], v[176:179], v[116:119]
	v_mfma_f32_16x16x32_bf16 v[112:115], v[168:171], v[176:179], v[112:115]
	v_mfma_f32_16x16x32_bf16 v[100:103], v[148:151], v[204:207], v[100:103]
	v_mfma_f32_16x16x32_bf16 v[96:99], v[168:171], v[204:207], v[96:99]
	v_mfma_f32_16x16x32_bf16 v[84:87], v[148:151], v[212:215], v[84:87]
	v_mfma_f32_16x16x32_bf16 v[80:83], v[168:171], v[212:215], v[80:83]
	v_mfma_f32_16x16x32_bf16 v[68:71], v[148:151], v[220:223], v[68:71]
	v_mfma_f32_16x16x32_bf16 v[64:67], v[168:171], v[220:223], v[64:67]
	v_mfma_f32_16x16x32_bf16 v[116:119], v[164:167], v[186:189], v[116:119]
	v_mfma_f32_16x16x32_bf16 v[112:115], v[172:175], v[186:189], v[112:115]
	v_mfma_f32_16x16x32_bf16 v[100:103], v[164:167], v[208:211], v[100:103]
	v_mfma_f32_16x16x32_bf16 v[96:99], v[172:175], v[208:211], v[96:99]
	v_mfma_f32_16x16x32_bf16 v[84:87], v[164:167], v[216:219], v[84:87]
	v_mfma_f32_16x16x32_bf16 v[80:83], v[172:175], v[216:219], v[80:83]
	v_mfma_f32_16x16x32_bf16 v[68:71], v[164:167], v[224:227], v[68:71]
	v_mfma_f32_16x16x32_bf16 v[64:67], v[172:175], v[224:227], v[64:67]
	s_setprio 0
	s_barrier
	ds_read_b128 v[176:179], v185 offset:16384
	ds_read_b128 v[186:189], v185 offset:17408
	s_add_u32 s60, s28, 0x40000
	s_addc_u32 s61, s29, 0
	s_add_i32 m0, s59, s38
	ds_read_b128 v[204:207], v185 offset:18432
	global_load_lds_dwordx4 v154, s[28:29]
	s_add_i32 m0, m0, 0x2000
	ds_read_b128 v[208:211], v185 offset:19456
	global_load_lds_dwordx4 v158, s[28:29]
	s_add_i32 m0, s62, s38
	ds_read_b128 v[212:215], v185 offset:20480
	global_load_lds_dwordx4 v154, s[60:61]
	s_add_i32 m0, m0, 0x2000
	ds_read_b128 v[216:219], v185 offset:21504
	global_load_lds_dwordx4 v158, s[60:61]
	s_mov_b32 m0, s21
	ds_read_b128 v[220:223], v185 offset:22528
	global_load_lds_dwordx4 v152, s[30:31]
	s_mov_b32 m0, s23
	ds_read_b128 v[224:227], v185 offset:23552
	global_load_lds_dwordx4 v156, s[30:31]
	s_cmp_lg_i32 s63, 0
	s_cbranch_scc1 .Lpg8rx5
	s_waitcnt vmcnt(8)
; #define PG8_STAGE(bufoff, gbase, voff) do { _Pragma("unroll") for (int _i = 0; _i < 2; ++_i) \
;         __builtin_amdgcn_global_load_lds((const unsigned*)((const char*)(gbase) + (voff)[_i]), (PG8_LAS unsigned*)(lds + (bufoff) + ldsw + _i * 8192), 16, 0, 0); } while (0)
; #define PG8_LDA(dst, b, h) do { _Pragma("unroll") for (int m = 0; m < 4; ++m) _Pragma("unroll") for (int k = 0; k < 2; ++k) dst[m][k] = *(const PG8_LAS bf16x8*)(lds + PG8_SA(b, h) + aoff + m * 2048 + k * 1024); } while (0)
; #define PG8_LDB(dst, b, h) do { _Pragma("unroll") for (int n = 0; n < 2; ++n) _Pragma("unroll") for (int k = 0; k < 2; ++k) dst[n][k] = *(const PG8_LAS bf16x8*)(lds + PG8_SB(b, h) + boff + n * 2048 + k * 1024); } while (0)
; #define PG8_MMA(ai, bj, At, Bt) do { __builtin_amdgcn_s_setprio(1); _Pragma("unroll") for (int m = 0; m < 4; ++m) _Pragma("unroll") for (int n = 0; n < 2; ++n) _Pragma("unroll") for (int k = 0; k < 2; ++k) \
;         acc[ai][bj][m][n] = __builtin_amdgcn_mfma_f32_16x16x32_bf16(Bt[n][k], At[m][k], acc[ai][bj][m][n], 0, 0, 0); __builtin_amdgcn_s_setprio(0); } while (0)
; #define PG8_WAIT_V(n) asm volatile("s_waitcnt vmcnt(" #n ")" ::: "memory")
; #define PG8_WAIT_L(n) asm volatile("s_waitcnt lgkmcnt(" #n ")" ::: "memory")
; #define PG8_WAIT_V8_UNLESS(flag) asm volatile("s_cmp_lg_i32 %0, 0\n\ts_cbranch_scc1 .Lpg8rx%=\n\ts_waitcnt vmcnt(8)\n.Lpg8rx%=:" :: "s"(__builtin_amdgcn_readfirstlane(flag)) : "scc", "memory")
; #define PG8_BAR __builtin_amdgcn_s_barrier()
; #define PG8_SCHED __builtin_amdgcn_sched_barrier(0)
; template <class Epi, class Sched, bool ALIGN_EPI = false, bool SP2 = false>
; __device__ __forceinline__ void gemm_phase(PG8_LAS unsigned char* lds, const Gemm g, const Sched& S, const Epi& E) {
;     ...
;             PG8_WAIT_V8_UNLESS(rx); PG8_WAIT_L(0); PG8_BAR; PG8_MMA(1, 0, At, B0); PG8_MMA(1, 1, At, B1); PG8_BAR; PG8_SCHED;
;             PG8_STAGE(PG8_SA(0, 1), a2 + hstep, voffA); PG8_SCHED; PG8_LDB(B0, 1, 0); PG8_LDB(B1, 1, 1); PG8_SCHED; PG8_LDA(At, 1, 0);
;             PG8_WAIT_V(8); PG8_WAIT_L(0); PG8_BAR; PG8_MMA(0, 0, At, B0); PG8_MMA(0, 1, At, B1); PG8_BAR; PG8_SCHED;
.Lpg8rx5:
	s_waitcnt lgkmcnt(0)
	s_setprio 1
	s_barrier
	v_mfma_f32_16x16x32_bf16 v[60:63], v[132:135], v[176:179], v[60:63]
	v_mfma_f32_16x16x32_bf16 v[56:59], v[140:143], v[176:179], v[56:59]
	v_mfma_f32_16x16x32_bf16 v[44:47], v[132:135], v[204:207], v[44:47]
	v_mfma_f32_16x16x32_bf16 v[40:43], v[140:143], v[204:207], v[40:43]
	v_mfma_f32_16x16x32_bf16 v[28:31], v[132:135], v[212:215], v[28:31]
	v_mfma_f32_16x16x32_bf16 v[24:27], v[140:143], v[212:215], v[24:27]
	v_mfma_f32_16x16x32_bf16 v[12:15], v[132:135], v[220:223], v[12:15]
	v_mfma_f32_16x16x32_bf16 v[8:11], v[140:143], v[220:223], v[8:11]
	v_mfma_f32_16x16x32_bf16 v[60:63], v[136:139], v[186:189], v[60:63]
	v_mfma_f32_16x16x32_bf16 v[56:59], v[144:147], v[186:189], v[56:59]
	v_mfma_f32_16x16x32_bf16 v[44:47], v[136:139], v[208:211], v[44:47]
	v_mfma_f32_16x16x32_bf16 v[40:43], v[144:147], v[208:211], v[40:43]
	v_mfma_f32_16x16x32_bf16 v[28:31], v[136:139], v[216:219], v[28:31]
	v_mfma_f32_16x16x32_bf16 v[24:27], v[144:147], v[216:219], v[24:27]
	v_mfma_f32_16x16x32_bf16 v[12:15], v[136:139], v[224:227], v[12:15]
	v_mfma_f32_16x16x32_bf16 v[8:11], v[144:147], v[224:227], v[8:11]
	v_mfma_f32_16x16x32_bf16 v[52:55], v[148:151], v[176:179], v[52:55]
	v_mfma_f32_16x16x32_bf16 v[48:51], v[168:171], v[176:179], v[48:51]
	v_mfma_f32_16x16x32_bf16 v[36:39], v[148:151], v[204:207], v[36:39]
	v_mfma_f32_16x16x32_bf16 v[32:35], v[168:171], v[204:207], v[32:35]
	v_mfma_f32_16x16x32_bf16 v[20:23], v[148:151], v[212:215], v[20:23]
	v_mfma_f32_16x16x32_bf16 v[16:19], v[168:171], v[212:215], v[16:19]
	v_mfma_f32_16x16x32_bf16 v[4:7], v[148:151], v[220:223], v[4:7]
	v_mfma_f32_16x16x32_bf16 v[0:3], v[168:171], v[220:223], v[0:3]
	v_mfma_f32_16x16x32_bf16 v[52:55], v[164:167], v[186:189], v[52:55]
	v_mfma_f32_16x16x32_bf16 v[48:51], v[172:175], v[186:189], v[48:51]
	v_mfma_f32_16x16x32_bf16 v[36:39], v[164:167], v[208:211], v[36:39]
	v_mfma_f32_16x16x32_bf16 v[32:35], v[172:175], v[208:211], v[32:35]
	v_mfma_f32_16x16x32_bf16 v[20:23], v[164:167], v[216:219], v[20:23]
	v_mfma_f32_16x16x32_bf16 v[16:19], v[172:175], v[216:219], v[16:19]
	v_mfma_f32_16x16x32_bf16 v[4:7], v[164:167], v[224:227], v[4:7]
	v_mfma_f32_16x16x32_bf16 v[0:3], v[172:175], v[224:227], v[0:3]
	s_setprio 0
	s_barrier
	s_mov_b64 s[98:99], s[30:31]
	s_add_u32 s100, s30, 0x40000
	s_addc_u32 s101, s31, 0
	s_add_i32 s30, 0, 0x18000
	s_add_i32 s31, 0, 0x1c000
	v_add_u32_e32 v144, s30, v183
	v_add_u32_e32 v172, s31, v183
	ds_read_b128 v[132:135], v144
	ds_read_b128 v[136:139], v144 offset:1024
	ds_read_b128 v[140:143], v144 offset:2048
	ds_read_b128 v[144:147], v144 offset:3072
	ds_read_b128 v[148:151], v172
	ds_read_b128 v[164:167], v172 offset:1024
	ds_read_b128 v[168:171], v172 offset:2048
	ds_read_b128 v[172:175], v172 offset:3072
	ds_read_b128 v[176:179], v185 offset:32768
	ds_read_b128 v[186:189], v185 offset:33792
	ds_read_b128 v[204:207], v185 offset:34816
	ds_read_b128 v[208:211], v185 offset:35840
	ds_read_b128 v[212:215], v185 offset:36864
	ds_read_b128 v[216:219], v185 offset:37888
	s_mov_b32 m0, s46
	ds_read_b128 v[220:223], v185 offset:38912
	global_load_lds_dwordx4 v152, s[100:101]
	s_mov_b32 m0, s48
	ds_read_b128 v[224:227], v185 offset:39936
	global_load_lds_dwordx4 v156, s[100:101]
	s_waitcnt vmcnt(8)
	s_waitcnt lgkmcnt(0)
	s_setprio 1
	s_barrier
	v_mfma_f32_16x16x32_bf16 v[124:127], v[132:135], v[176:179], v[124:127]
	v_mfma_f32_16x16x32_bf16 v[120:123], v[140:143], v[176:179], v[120:123]
	v_mfma_f32_16x16x32_bf16 v[108:111], v[132:135], v[204:207], v[108:111]
	v_mfma_f32_16x16x32_bf16 v[104:107], v[140:143], v[204:207], v[104:107]
	v_mfma_f32_16x16x32_bf16 v[92:95], v[132:135], v[212:215], v[92:95]
	v_mfma_f32_16x16x32_bf16 v[88:91], v[140:143], v[212:215], v[88:91]
	v_mfma_f32_16x16x32_bf16 v[76:79], v[132:135], v[220:223], v[76:79]
	v_mfma_f32_16x16x32_bf16 v[72:75], v[140:143], v[220:223], v[72:75]
	v_mfma_f32_16x16x32_bf16 v[124:127], v[136:139], v[186:189], v[124:127]
	v_mfma_f32_16x16x32_bf16 v[120:123], v[144:147], v[186:189], v[120:123]
	v_mfma_f32_16x16x32_bf16 v[108:111], v[136:139], v[208:211], v[108:111]
	v_mfma_f32_16x16x32_bf16 v[104:107], v[144:147], v[208:211], v[104:107]
	v_mfma_f32_16x16x32_bf16 v[92:95], v[136:139], v[216:219], v[92:95]
	v_mfma_f32_16x16x32_bf16 v[88:91], v[144:147], v[216:219], v[88:91]
	v_mfma_f32_16x16x32_bf16 v[76:79], v[136:139], v[224:227], v[76:79]
	v_mfma_f32_16x16x32_bf16 v[72:75], v[144:147], v[224:227], v[72:75]
	v_mfma_f32_16x16x32_bf16 v[116:119], v[148:151], v[176:179], v[116:119]
	v_mfma_f32_16x16x32_bf16 v[112:115], v[168:171], v[176:179], v[112:115]
	v_mfma_f32_16x16x32_bf16 v[100:103], v[148:151], v[204:207], v[100:103]
	v_mfma_f32_16x16x32_bf16 v[96:99], v[168:171], v[204:207], v[96:99]
	v_mfma_f32_16x16x32_bf16 v[84:87], v[148:151], v[212:215], v[84:87]
	v_mfma_f32_16x16x32_bf16 v[80:83], v[168:171], v[212:215], v[80:83]
	v_mfma_f32_16x16x32_bf16 v[68:71], v[148:151], v[220:223], v[68:71]
	v_mfma_f32_16x16x32_bf16 v[64:67], v[168:171], v[220:223], v[64:67]
	v_mfma_f32_16x16x32_bf16 v[116:119], v[164:167], v[186:189], v[116:119]
	v_mfma_f32_16x16x32_bf16 v[112:115], v[172:175], v[186:189], v[112:115]
	v_mfma_f32_16x16x32_bf16 v[100:103], v[164:167], v[208:211], v[100:103]
	v_mfma_f32_16x16x32_bf16 v[96:99], v[172:175], v[208:211], v[96:99]
	v_mfma_f32_16x16x32_bf16 v[84:87], v[164:167], v[216:219], v[84:87]
	v_mfma_f32_16x16x32_bf16 v[80:83], v[172:175], v[216:219], v[80:83]
	v_mfma_f32_16x16x32_bf16 v[68:71], v[164:167], v[224:227], v[68:71]
	v_mfma_f32_16x16x32_bf16 v[64:67], v[172:175], v[224:227], v[64:67]
	s_setprio 0
	s_barrier
; #define PG8_STAGE(bufoff, gbase, voff) do { _Pragma("unroll") for (int _i = 0; _i < 2; ++_i) \
;         __builtin_amdgcn_global_load_lds((const unsigned*)((const char*)(gbase) + (voff)[_i]), (PG8_LAS unsigned*)(lds + (bufoff) + ldsw + _i * 8192), 16, 0, 0); } while (0)
; #define PG8_LDA(dst, b, h) do { _Pragma("unroll") for (int m = 0; m < 4; ++m) _Pragma("unroll") for (int k = 0; k < 2; ++k) dst[m][k] = *(const PG8_LAS bf16x8*)(lds + PG8_SA(b, h) + aoff + m * 2048 + k * 1024); } while (0)
; #define PG8_MMA(ai, bj, At, Bt) do { __builtin_amdgcn_s_setprio(1); _Pragma("unroll") for (int m = 0; m < 4; ++m) _Pragma("unroll") for (int n = 0; n < 2; ++n) _Pragma("unroll") for (int k = 0; k < 2; ++k) \
;         acc[ai][bj][m][n] = __builtin_amdgcn_mfma_f32_16x16x32_bf16(Bt[n][k], At[m][k], acc[ai][bj][m][n], 0, 0, 0); __builtin_amdgcn_s_setprio(0); } while (0)
; #define PG8_WAIT_V(n) asm volatile("s_waitcnt vmcnt(" #n ")" ::: "memory")
; #define PG8_WAIT_L(n) asm volatile("s_waitcnt lgkmcnt(" #n ")" ::: "memory")
; #define PG8_BAR __builtin_amdgcn_s_barrier()
; #define PG8_SCHED __builtin_amdgcn_sched_barrier(0)
; template <class Epi, class Sched, bool ALIGN_EPI = false, bool SP2 = false>
; __device__ __forceinline__ void gemm_phase(PG8_LAS unsigned char* lds, const Gemm g, const Sched& S, const Epi& E) {
;     ...
;             PG8_STAGE(PG8_SB(1, 0), b3, voffB); PG8_STAGE(PG8_SB(1, 1), b3 + hstep, voffB); PG8_STAGE(PG8_SA(1, 0), a3, voffA); PG8_SCHED; PG8_LDA(At, 1, 1);
;             PG8_WAIT_V(8); PG8_WAIT_L(0); PG8_BAR; PG8_MMA(1, 0, At, B0); PG8_MMA(1, 1, At, B1); PG8_BAR; PG8_SCHED;
;     ...
;         if constexpr (ALIGN_EPI) { if (wr == 0) PG8_BAR; }
	ds_read_b128 v[176:179], v185 offset:49152
	ds_read_b128 v[186:189], v185 offset:50176
	s_add_u32 s100, s28, 0x80
	s_addc_u32 s101, s29, 0
	s_add_u32 s28, s28, 0x40080
	s_addc_u32 s29, s29, 0
	s_add_u32 s98, s98, 0x80
	s_addc_u32 s99, s99, 0
	s_add_i32 m0, s30, s38
	ds_read_b128 v[204:207], v185 offset:51200
	global_load_lds_dwordx4 v154, s[100:101]
	s_add_i32 m0, m0, 0x2000
	ds_read_b128 v[208:211], v185 offset:52224
	global_load_lds_dwordx4 v158, s[100:101]
	s_add_i32 m0, s31, s38
	ds_read_b128 v[212:215], v185 offset:53248
	global_load_lds_dwordx4 v154, s[28:29]
	s_add_i32 m0, m0, 0x2000
	ds_read_b128 v[216:219], v185 offset:54272
	global_load_lds_dwordx4 v158, s[28:29]
	s_mov_b32 m0, s50
	ds_read_b128 v[220:223], v185 offset:55296
	global_load_lds_dwordx4 v152, s[98:99]
	s_mov_b32 m0, s51
	ds_read_b128 v[224:227], v185 offset:56320
	global_load_lds_dwordx4 v156, s[98:99]
	s_waitcnt vmcnt(8)
	s_waitcnt lgkmcnt(0)
	s_setprio 1
	s_barrier
	v_mfma_f32_16x16x32_bf16 v[60:63], v[132:135], v[176:179], v[60:63]
	v_mfma_f32_16x16x32_bf16 v[56:59], v[140:143], v[176:179], v[56:59]
	v_mfma_f32_16x16x32_bf16 v[44:47], v[132:135], v[204:207], v[44:47]
	v_mfma_f32_16x16x32_bf16 v[40:43], v[140:143], v[204:207], v[40:43]
	v_mfma_f32_16x16x32_bf16 v[28:31], v[132:135], v[212:215], v[28:31]
	v_mfma_f32_16x16x32_bf16 v[24:27], v[140:143], v[212:215], v[24:27]
	v_mfma_f32_16x16x32_bf16 v[12:15], v[132:135], v[220:223], v[12:15]
	v_mfma_f32_16x16x32_bf16 v[8:11], v[140:143], v[220:223], v[8:11]
	v_mfma_f32_16x16x32_bf16 v[60:63], v[136:139], v[186:189], v[60:63]
	v_mfma_f32_16x16x32_bf16 v[56:59], v[144:147], v[186:189], v[56:59]
	v_mfma_f32_16x16x32_bf16 v[44:47], v[136:139], v[208:211], v[44:47]
	v_mfma_f32_16x16x32_bf16 v[40:43], v[144:147], v[208:211], v[40:43]
	v_mfma_f32_16x16x32_bf16 v[28:31], v[136:139], v[216:219], v[28:31]
	v_mfma_f32_16x16x32_bf16 v[24:27], v[144:147], v[216:219], v[24:27]
	v_mfma_f32_16x16x32_bf16 v[12:15], v[136:139], v[224:227], v[12:15]
	v_mfma_f32_16x16x32_bf16 v[8:11], v[144:147], v[224:227], v[8:11]
	v_mfma_f32_16x16x32_bf16 v[52:55], v[148:151], v[176:179], v[52:55]
	v_mfma_f32_16x16x32_bf16 v[48:51], v[168:171], v[176:179], v[48:51]
	v_mfma_f32_16x16x32_bf16 v[36:39], v[148:151], v[204:207], v[36:39]
	v_mfma_f32_16x16x32_bf16 v[32:35], v[168:171], v[204:207], v[32:35]
	v_mfma_f32_16x16x32_bf16 v[20:23], v[148:151], v[212:215], v[20:23]
	v_mfma_f32_16x16x32_bf16 v[16:19], v[168:171], v[212:215], v[16:19]
	v_mfma_f32_16x16x32_bf16 v[4:7], v[148:151], v[220:223], v[4:7]
	v_mfma_f32_16x16x32_bf16 v[0:3], v[168:171], v[220:223], v[0:3]
	v_mfma_f32_16x16x32_bf16 v[52:55], v[164:167], v[186:189], v[52:55]
	v_mfma_f32_16x16x32_bf16 v[48:51], v[172:175], v[186:189], v[48:51]
	v_mfma_f32_16x16x32_bf16 v[36:39], v[164:167], v[208:211], v[36:39]
	v_mfma_f32_16x16x32_bf16 v[32:35], v[172:175], v[208:211], v[32:35]
	v_mfma_f32_16x16x32_bf16 v[20:23], v[164:167], v[216:219], v[20:23]
	v_mfma_f32_16x16x32_bf16 v[16:19], v[172:175], v[216:219], v[16:19]
	v_mfma_f32_16x16x32_bf16 v[4:7], v[164:167], v[224:227], v[4:7]
	v_mfma_f32_16x16x32_bf16 v[0:3], v[172:175], v[224:227], v[0:3]
	s_setprio 0
	s_barrier
	s_add_i32 s58, s58, 2
	s_add_u32 s40, s40, 0x100
	s_addc_u32 s41, s41, 0
	s_cmp_gt_u32 s58, 13
	s_cbranch_scc0 .LBB0_611
	s_and_b64 vcc, exec, s[8:9]
	s_cbranch_vccz .LBB0_614
	s_barrier

; #define PG8_STAGE(bufoff, gbase, voff) do { _Pragma("unroll") for (int _i = 0; _i < 2; ++_i) \
;         __builtin_amdgcn_global_load_lds((const unsigned*)((const char*)(gbase) + (voff)[_i]), (PG8_LAS unsigned*)(lds + (bufoff) + ldsw + _i * 8192), 16, 0, 0); } while (0)
; #define PG8_LDA(dst, b, h) do { _Pragma("unroll") for (int m = 0; m < 4; ++m) _Pragma("unroll") for (int k = 0; k < 2; ++k) dst[m][k] = *(const PG8_LAS bf16x8*)(lds + PG8_SA(b, h) + aoff + m * 2048 + k * 1024); } while (0)
; #define PG8_LDB(dst, b, h) do { _Pragma("unroll") for (int n = 0; n < 2; ++n) _Pragma("unroll") for (int k = 0; k < 2; ++k) dst[n][k] = *(const PG8_LAS bf16x8*)(lds + PG8_SB(b, h) + boff + n * 2048 + k * 1024); } while (0)
; #define PG8_MMA(ai, bj, At, Bt) do { __builtin_amdgcn_s_setprio(1); _Pragma("unroll") for (int m = 0; m < 4; ++m) _Pragma("unroll") for (int n = 0; n < 2; ++n) _Pragma("unroll") for (int k = 0; k < 2; ++k) \
;         acc[ai][bj][m][n] = __builtin_amdgcn_mfma_f32_16x16x32_bf16(Bt[n][k], At[m][k], acc[ai][bj][m][n], 0, 0, 0); __builtin_amdgcn_s_setprio(0); } while (0)
; #define PG8_WAIT_L(n) asm volatile("s_waitcnt lgkmcnt(" #n ")" ::: "memory")
; template <class Epi, class Sched, bool ALIGN_EPI = false, bool SP2 = false>
; __device__ __forceinline__ void gemm_phase(PG8_LAS unsigned char* lds, const Gemm g, const Sched& S, const Epi& E) {
;     ...
;             const bool last = (t == nt - 2);
;             const char* a1 = cA + (size_t)(t + 1) * kstep;
;             const char* a2 = last ? nA : cA + (size_t)(t + 2) * kstep; const char* b2 = last ? nB : cB + (size_t)(t + 2) * kstep;
;             const char* a3 = a2 + kstep; const char* b3 = b2 + kstep;
;             if (last && has_next) S.a_ready(nxt);
;             if constexpr (SP2) {
;             const int rx = (relax && t == 0) ? 1 : 0;
;             PG8_STAGE(PG8_SA(1, 1), a1 + hstep, voffA); PG8_SCHED; PG8_LDB(B0, 0, 0); PG8_LDB(B1, 0, 1); PG8_SCHED; PG8_LDA(At, 0, 0);
;             PG8_WAIT_V8_UNLESS(rx); PG8_WAIT_L(0); PG8_BAR; PG8_MMA(0, 0, At, B0); PG8_MMA(0, 1, At, B1); PG8_BAR; PG8_SCHED;
;             PG8_STAGE(PG8_SB(0, 0), b2, voffB); PG8_STAGE(PG8_SB(0, 1), b2 + hstep, voffB); PG8_STAGE(PG8_SA(0, 0), a2, voffA); PG8_SCHED; PG8_LDA(At, 0, 1);
;             PG8_WAIT_V8_UNLESS(rx); PG8_WAIT_L(0); PG8_BAR; PG8_MMA(1, 0, At, B0); PG8_MMA(1, 1, At, B1); PG8_BAR; PG8_SCHED;
.LBB0_965:
	s_add_u32 s28, s0, s40
	s_addc_u32 s29, s1, s41
	s_add_u32 s30, s28, 0x100
	s_addc_u32 s31, s29, 0
	s_add_u32 s98, s28, 0x100080
	s_addc_u32 s99, s29, 0
	s_add_u32 s57, s54, s40
	s_addc_u32 s60, s55, s41
	s_cmp_eq_u32 s40, 0
	s_cselect_b64 s[28:29], -1, 0
	s_and_b64 s[58:59], s[26:27], s[28:29]
	s_cmpk_eq_i32 s40, 0x1f00
	s_cselect_b32 s31, s15, s31
	s_cselect_b32 s30, s23, s30
	s_cselect_b32 s29, s13, s60
	s_cselect_b32 s28, s53, s57
	s_add_i32 s57, 0, 0x10000
	s_add_i32 s60, 0, 0x14000
	v_add_u32_e32 v136, s57, v247
	v_add_u32_e32 v160, s60, v247
	ds_read_b128 v[120:123], v136
	ds_read_b128 v[128:131], v136 offset:1024
	ds_read_b128 v[132:135], v136 offset:2048
	ds_read_b128 v[136:139], v136 offset:3072
	ds_read_b128 v[140:143], v160
	ds_read_b128 v[144:147], v160 offset:1024
	ds_read_b128 v[156:159], v160 offset:2048
	ds_read_b128 v[160:163], v160 offset:3072
	ds_read_b128 v[164:167], v248
	ds_read_b128 v[168:171], v248 offset:1024
	ds_read_b128 v[172:175], v248 offset:2048
	ds_read_b128 v[176:179], v248 offset:3072
	ds_read_b128 v[180:183], v248 offset:4096
	ds_read_b128 v[184:187], v248 offset:5120
	ds_read_b128 v[188:191], v248 offset:6144
	s_add_i32 m0, s25, 0xc000
	s_and_b32 s61, s58, 1
	global_load_lds_dwordx4 v204, s[98:99]
	s_add_i32 m0, s25, 0xe000
	ds_read_b128 v[214:217], v248 offset:7168
	global_load_lds_dwordx4 v206, s[98:99]
	s_cmp_lg_i32 s61, 0
	s_cbranch_scc1 .Lpg8rx6
	s_waitcnt vmcnt(8)
.Lpg8rx6:
	s_waitcnt lgkmcnt(0)
	s_setprio 1
	s_barrier
	v_mfma_f32_16x16x32_bf16 v[152:155], v[120:123], v[164:167], v[152:155]
	v_mfma_f32_16x16x32_bf16 v[148:151], v[132:135], v[164:167], v[148:151]
	v_mfma_f32_16x16x32_bf16 v[108:111], v[120:123], v[172:175], v[108:111]
	v_mfma_f32_16x16x32_bf16 v[104:107], v[132:135], v[172:175], v[104:107]
	v_mfma_f32_16x16x32_bf16 v[92:95], v[120:123], v[180:183], v[92:95]
	v_mfma_f32_16x16x32_bf16 v[88:91], v[132:135], v[180:183], v[88:91]
	v_mfma_f32_16x16x32_bf16 v[76:79], v[120:123], v[188:191], v[76:79]
	v_mfma_f32_16x16x32_bf16 v[72:75], v[132:135], v[188:191], v[72:75]
	v_mfma_f32_16x16x32_bf16 v[152:155], v[128:131], v[168:171], v[152:155]
	v_mfma_f32_16x16x32_bf16 v[148:151], v[136:139], v[168:171], v[148:151]
	v_mfma_f32_16x16x32_bf16 v[108:111], v[128:131], v[176:179], v[108:111]
	v_mfma_f32_16x16x32_bf16 v[104:107], v[136:139], v[176:179], v[104:107]
	v_mfma_f32_16x16x32_bf16 v[92:95], v[128:131], v[184:187], v[92:95]
	v_mfma_f32_16x16x32_bf16 v[88:91], v[136:139], v[184:187], v[88:91]
	v_mfma_f32_16x16x32_bf16 v[76:79], v[128:131], v[214:217], v[76:79]
	v_mfma_f32_16x16x32_bf16 v[72:75], v[136:139], v[214:217], v[72:75]
	v_mfma_f32_16x16x32_bf16 v[124:127], v[140:143], v[164:167], v[124:127]
	v_mfma_f32_16x16x32_bf16 v[112:115], v[156:159], v[164:167], v[112:115]
	v_mfma_f32_16x16x32_bf16 v[100:103], v[140:143], v[172:175], v[100:103]
	v_mfma_f32_16x16x32_bf16 v[96:99], v[156:159], v[172:175], v[96:99]
	v_mfma_f32_16x16x32_bf16 v[84:87], v[140:143], v[180:183], v[84:87]
	v_mfma_f32_16x16x32_bf16 v[80:83], v[156:159], v[180:183], v[80:83]
	v_mfma_f32_16x16x32_bf16 v[68:71], v[140:143], v[188:191], v[68:71]
	v_mfma_f32_16x16x32_bf16 v[64:67], v[156:159], v[188:191], v[64:67]
	v_mfma_f32_16x16x32_bf16 v[124:127], v[144:147], v[168:171], v[124:127]
	v_mfma_f32_16x16x32_bf16 v[112:115], v[160:163], v[168:171], v[112:115]
	v_mfma_f32_16x16x32_bf16 v[100:103], v[144:147], v[176:179], v[100:103]
	v_mfma_f32_16x16x32_bf16 v[96:99], v[160:163], v[176:179], v[96:99]
	v_mfma_f32_16x16x32_bf16 v[84:87], v[144:147], v[184:187], v[84:87]
	v_mfma_f32_16x16x32_bf16 v[80:83], v[160:163], v[184:187], v[80:83]
	v_mfma_f32_16x16x32_bf16 v[68:71], v[144:147], v[214:217], v[68:71]
	v_mfma_f32_16x16x32_bf16 v[64:67], v[160:163], v[214:217], v[64:67]
	s_setprio 0
	s_barrier
	ds_read_b128 v[164:167], v248 offset:16384
	ds_read_b128 v[168:171], v248 offset:17408
	s_add_u32 s58, s28, 0x100000
	s_addc_u32 s59, s29, 0
	s_add_i32 m0, s57, s39
	ds_read_b128 v[172:175], v248 offset:18432
	global_load_lds_dwordx4 v194, s[28:29]
	s_add_i32 m0, m0, 0x2000
	ds_read_b128 v[176:179], v248 offset:19456
	global_load_lds_dwordx4 v208, s[28:29]
	s_add_i32 m0, s60, s39
	ds_read_b128 v[180:183], v248 offset:20480
	global_load_lds_dwordx4 v194, s[58:59]
	s_add_i32 m0, m0, 0x2000
	ds_read_b128 v[184:187], v248 offset:21504
	global_load_lds_dwordx4 v208, s[58:59]
	s_mov_b32 m0, s25
	ds_read_b128 v[188:191], v248 offset:22528
	global_load_lds_dwordx4 v204, s[30:31]
	s_mov_b32 m0, s42
	ds_read_b128 v[214:217], v248 offset:23552
	global_load_lds_dwordx4 v206, s[30:31]
	s_cmp_lg_i32 s61, 0
	s_cbranch_scc1 .Lpg8rx7
	s_waitcnt vmcnt(8)
; #define PG8_STAGE(bufoff, gbase, voff) do { _Pragma("unroll") for (int _i = 0; _i < 2; ++_i) \
;         __builtin_amdgcn_global_load_lds((const unsigned*)((const char*)(gbase) + (voff)[_i]), (PG8_LAS unsigned*)(lds + (bufoff) + ldsw + _i * 8192), 16, 0, 0); } while (0)
; #define PG8_LDA(dst, b, h) do { _Pragma("unroll") for (int m = 0; m < 4; ++m) _Pragma("unroll") for (int k = 0; k < 2; ++k) dst[m][k] = *(const PG8_LAS bf16x8*)(lds + PG8_SA(b, h) + aoff + m * 2048 + k * 1024); } while (0)
; #define PG8_LDB(dst, b, h) do { _Pragma("unroll") for (int n = 0; n < 2; ++n) _Pragma("unroll") for (int k = 0; k < 2; ++k) dst[n][k] = *(const PG8_LAS bf16x8*)(lds + PG8_SB(b, h) + boff + n * 2048 + k * 1024); } while (0)
; #define PG8_MMA(ai, bj, At, Bt) do { __builtin_amdgcn_s_setprio(1); _Pragma("unroll") for (int m = 0; m < 4; ++m) _Pragma("unroll") for (int n = 0; n < 2; ++n) _Pragma("unroll") for (int k = 0; k < 2; ++k) \
;         acc[ai][bj][m][n] = __builtin_amdgcn_mfma_f32_16x16x32_bf16(Bt[n][k], At[m][k], acc[ai][bj][m][n], 0, 0, 0); __builtin_amdgcn_s_setprio(0); } while (0)
; #define PG8_WAIT_V(n) asm volatile("s_waitcnt vmcnt(" #n ")" ::: "memory")
; #define PG8_WAIT_L(n) asm volatile("s_waitcnt lgkmcnt(" #n ")" ::: "memory")
; #define PG8_WAIT_V8_UNLESS(flag) asm volatile("s_cmp_lg_i32 %0, 0\n\ts_cbranch_scc1 .Lpg8rx%=\n\ts_waitcnt vmcnt(8)\n.Lpg8rx%=:" :: "s"(__builtin_amdgcn_readfirstlane(flag)) : "scc", "memory")
; #define PG8_BAR __builtin_amdgcn_s_barrier()
; #define PG8_SCHED __builtin_amdgcn_sched_barrier(0)
; template <class Epi, class Sched, bool ALIGN_EPI = false, bool SP2 = false>
; __device__ __forceinline__ void gemm_phase(PG8_LAS unsigned char* lds, const Gemm g, const Sched& S, const Epi& E) {
;     ...
;             PG8_WAIT_V8_UNLESS(rx); PG8_WAIT_L(0); PG8_BAR; PG8_MMA(1, 0, At, B0); PG8_MMA(1, 1, At, B1); PG8_BAR; PG8_SCHED;
;             PG8_STAGE(PG8_SA(0, 1), a2 + hstep, voffA); PG8_SCHED; PG8_LDB(B0, 1, 0); PG8_LDB(B1, 1, 1); PG8_SCHED; PG8_LDA(At, 1, 0);
;             PG8_WAIT_V(8); PG8_WAIT_L(0); PG8_BAR; PG8_MMA(0, 0, At, B0); PG8_MMA(0, 1, At, B1); PG8_BAR; PG8_SCHED;
.Lpg8rx7:
	s_waitcnt lgkmcnt(0)
	s_setprio 1
	s_barrier
	v_mfma_f32_16x16x32_bf16 v[60:63], v[120:123], v[164:167], v[60:63]
	v_mfma_f32_16x16x32_bf16 v[56:59], v[132:135], v[164:167], v[56:59]
	v_mfma_f32_16x16x32_bf16 v[44:47], v[120:123], v[172:175], v[44:47]
	v_mfma_f32_16x16x32_bf16 v[40:43], v[132:135], v[172:175], v[40:43]
	v_mfma_f32_16x16x32_bf16 v[28:31], v[120:123], v[180:183], v[28:31]
	v_mfma_f32_16x16x32_bf16 v[24:27], v[132:135], v[180:183], v[24:27]
	v_mfma_f32_16x16x32_bf16 v[12:15], v[120:123], v[188:191], v[12:15]
	v_mfma_f32_16x16x32_bf16 v[8:11], v[132:135], v[188:191], v[8:11]
	v_mfma_f32_16x16x32_bf16 v[60:63], v[128:131], v[168:171], v[60:63]
	v_mfma_f32_16x16x32_bf16 v[56:59], v[136:139], v[168:171], v[56:59]
	v_mfma_f32_16x16x32_bf16 v[44:47], v[128:131], v[176:179], v[44:47]
	v_mfma_f32_16x16x32_bf16 v[40:43], v[136:139], v[176:179], v[40:43]
	v_mfma_f32_16x16x32_bf16 v[28:31], v[128:131], v[184:187], v[28:31]
	v_mfma_f32_16x16x32_bf16 v[24:27], v[136:139], v[184:187], v[24:27]
	v_mfma_f32_16x16x32_bf16 v[12:15], v[128:131], v[214:217], v[12:15]
	v_mfma_f32_16x16x32_bf16 v[8:11], v[136:139], v[214:217], v[8:11]
	v_mfma_f32_16x16x32_bf16 v[52:55], v[140:143], v[164:167], v[52:55]
	v_mfma_f32_16x16x32_bf16 v[48:51], v[156:159], v[164:167], v[48:51]
	v_mfma_f32_16x16x32_bf16 v[36:39], v[140:143], v[172:175], v[36:39]
	v_mfma_f32_16x16x32_bf16 v[32:35], v[156:159], v[172:175], v[32:35]
	v_mfma_f32_16x16x32_bf16 v[20:23], v[140:143], v[180:183], v[20:23]
	v_mfma_f32_16x16x32_bf16 v[16:19], v[156:159], v[180:183], v[16:19]
	v_mfma_f32_16x16x32_bf16 v[4:7], v[140:143], v[188:191], v[4:7]
	v_mfma_f32_16x16x32_bf16 v[0:3], v[156:159], v[188:191], v[0:3]
	v_mfma_f32_16x16x32_bf16 v[52:55], v[144:147], v[168:171], v[52:55]
	v_mfma_f32_16x16x32_bf16 v[48:51], v[160:163], v[168:171], v[48:51]
	v_mfma_f32_16x16x32_bf16 v[36:39], v[144:147], v[176:179], v[36:39]
	v_mfma_f32_16x16x32_bf16 v[32:35], v[160:163], v[176:179], v[32:35]
	v_mfma_f32_16x16x32_bf16 v[20:23], v[144:147], v[184:187], v[20:23]
	v_mfma_f32_16x16x32_bf16 v[16:19], v[160:163], v[184:187], v[16:19]
	v_mfma_f32_16x16x32_bf16 v[4:7], v[144:147], v[214:217], v[4:7]
	v_mfma_f32_16x16x32_bf16 v[0:3], v[160:163], v[214:217], v[0:3]
	s_setprio 0
	s_barrier
	s_mov_b64 s[98:99], s[30:31]
	s_add_u32 s100, s30, 0x100000
	s_addc_u32 s101, s31, 0
	s_add_i32 s30, 0, 0x18000
	s_add_i32 s31, 0, 0x1c000
	v_add_u32_e32 v136, s30, v247
	v_add_u32_e32 v160, s31, v247
	ds_read_b128 v[120:123], v136
	ds_read_b128 v[128:131], v136 offset:1024
	ds_read_b128 v[132:135], v136 offset:2048
	ds_read_b128 v[136:139], v136 offset:3072
	ds_read_b128 v[140:143], v160
	ds_read_b128 v[144:147], v160 offset:1024
	ds_read_b128 v[156:159], v160 offset:2048
	ds_read_b128 v[160:163], v160 offset:3072
	ds_read_b128 v[164:167], v248 offset:32768
	ds_read_b128 v[168:171], v248 offset:33792
	ds_read_b128 v[172:175], v248 offset:34816
	ds_read_b128 v[176:179], v248 offset:35840
	ds_read_b128 v[180:183], v248 offset:36864
	ds_read_b128 v[184:187], v248 offset:37888
	s_mov_b32 m0, s43
	ds_read_b128 v[188:191], v248 offset:38912
	global_load_lds_dwordx4 v204, s[100:101]
	s_mov_b32 m0, s44
	ds_read_b128 v[214:217], v248 offset:39936
	global_load_lds_dwordx4 v206, s[100:101]
	s_waitcnt vmcnt(8)
	s_waitcnt lgkmcnt(0)
	s_setprio 1
	s_barrier
	v_mfma_f32_16x16x32_bf16 v[152:155], v[120:123], v[164:167], v[152:155]
	v_mfma_f32_16x16x32_bf16 v[148:151], v[132:135], v[164:167], v[148:151]
	v_mfma_f32_16x16x32_bf16 v[108:111], v[120:123], v[172:175], v[108:111]
	v_mfma_f32_16x16x32_bf16 v[104:107], v[132:135], v[172:175], v[104:107]
	v_mfma_f32_16x16x32_bf16 v[92:95], v[120:123], v[180:183], v[92:95]
	v_mfma_f32_16x16x32_bf16 v[88:91], v[132:135], v[180:183], v[88:91]
	v_mfma_f32_16x16x32_bf16 v[76:79], v[120:123], v[188:191], v[76:79]
	v_mfma_f32_16x16x32_bf16 v[72:75], v[132:135], v[188:191], v[72:75]
	v_mfma_f32_16x16x32_bf16 v[152:155], v[128:131], v[168:171], v[152:155]
	v_mfma_f32_16x16x32_bf16 v[148:151], v[136:139], v[168:171], v[148:151]
	v_mfma_f32_16x16x32_bf16 v[108:111], v[128:131], v[176:179], v[108:111]
	v_mfma_f32_16x16x32_bf16 v[104:107], v[136:139], v[176:179], v[104:107]
	v_mfma_f32_16x16x32_bf16 v[92:95], v[128:131], v[184:187], v[92:95]
	v_mfma_f32_16x16x32_bf16 v[88:91], v[136:139], v[184:187], v[88:91]
	v_mfma_f32_16x16x32_bf16 v[76:79], v[128:131], v[214:217], v[76:79]
	v_mfma_f32_16x16x32_bf16 v[72:75], v[136:139], v[214:217], v[72:75]
	v_mfma_f32_16x16x32_bf16 v[124:127], v[140:143], v[164:167], v[124:127]
	v_mfma_f32_16x16x32_bf16 v[112:115], v[156:159], v[164:167], v[112:115]
	v_mfma_f32_16x16x32_bf16 v[100:103], v[140:143], v[172:175], v[100:103]
	v_mfma_f32_16x16x32_bf16 v[96:99], v[156:159], v[172:175], v[96:99]
	v_mfma_f32_16x16x32_bf16 v[84:87], v[140:143], v[180:183], v[84:87]
	v_mfma_f32_16x16x32_bf16 v[80:83], v[156:159], v[180:183], v[80:83]
	v_mfma_f32_16x16x32_bf16 v[68:71], v[140:143], v[188:191], v[68:71]
	v_mfma_f32_16x16x32_bf16 v[64:67], v[156:159], v[188:191], v[64:67]
	v_mfma_f32_16x16x32_bf16 v[124:127], v[144:147], v[168:171], v[124:127]
	v_mfma_f32_16x16x32_bf16 v[112:115], v[160:163], v[168:171], v[112:115]
	v_mfma_f32_16x16x32_bf16 v[100:103], v[144:147], v[176:179], v[100:103]
	v_mfma_f32_16x16x32_bf16 v[96:99], v[160:163], v[176:179], v[96:99]
	v_mfma_f32_16x16x32_bf16 v[84:87], v[144:147], v[184:187], v[84:87]
	v_mfma_f32_16x16x32_bf16 v[80:83], v[160:163], v[184:187], v[80:83]
	v_mfma_f32_16x16x32_bf16 v[68:71], v[144:147], v[214:217], v[68:71]
	v_mfma_f32_16x16x32_bf16 v[64:67], v[160:163], v[214:217], v[64:67]
	s_setprio 0
	s_barrier
; #define PG8_STAGE(bufoff, gbase, voff) do { _Pragma("unroll") for (int _i = 0; _i < 2; ++_i) \
;         __builtin_amdgcn_global_load_lds((const unsigned*)((const char*)(gbase) + (voff)[_i]), (PG8_LAS unsigned*)(lds + (bufoff) + ldsw + _i * 8192), 16, 0, 0); } while (0)
; #define PG8_LDA(dst, b, h) do { _Pragma("unroll") for (int m = 0; m < 4; ++m) _Pragma("unroll") for (int k = 0; k < 2; ++k) dst[m][k] = *(const PG8_LAS bf16x8*)(lds + PG8_SA(b, h) + aoff + m * 2048 + k * 1024); } while (0)
; #define PG8_MMA(ai, bj, At, Bt) do { __builtin_amdgcn_s_setprio(1); _Pragma("unroll") for (int m = 0; m < 4; ++m) _Pragma("unroll") for (int n = 0; n < 2; ++n) _Pragma("unroll") for (int k = 0; k < 2; ++k) \
;         acc[ai][bj][m][n] = __builtin_amdgcn_mfma_f32_16x16x32_bf16(Bt[n][k], At[m][k], acc[ai][bj][m][n], 0, 0, 0); __builtin_amdgcn_s_setprio(0); } while (0)
; #define PG8_WAIT_V(n) asm volatile("s_waitcnt vmcnt(" #n ")" ::: "memory")
; #define PG8_WAIT_L(n) asm volatile("s_waitcnt lgkmcnt(" #n ")" ::: "memory")
; #define PG8_BAR __builtin_amdgcn_s_barrier()
; #define PG8_SCHED __builtin_amdgcn_sched_barrier(0)
; template <class Epi, class Sched, bool ALIGN_EPI = false, bool SP2 = false>
; __device__ __forceinline__ void gemm_phase(PG8_LAS unsigned char* lds, const Gemm g, const Sched& S, const Epi& E) {
;     ...
;             PG8_STAGE(PG8_SB(1, 0), b3, voffB); PG8_STAGE(PG8_SB(1, 1), b3 + hstep, voffB); PG8_STAGE(PG8_SA(1, 0), a3, voffA); PG8_SCHED; PG8_LDA(At, 1, 1);
;             PG8_WAIT_V(8); PG8_WAIT_L(0); PG8_BAR; PG8_MMA(1, 0, At, B0); PG8_MMA(1, 1, At, B1); PG8_BAR; PG8_SCHED;
;     ...
;         if constexpr (ALIGN_EPI) { if (wr == 0) PG8_BAR; }
	ds_read_b128 v[164:167], v248 offset:49152
	ds_read_b128 v[168:171], v248 offset:50176
	s_add_u32 s100, s28, 0x80
	s_addc_u32 s101, s29, 0
	s_add_u32 s28, s28, 0x100080
	s_addc_u32 s29, s29, 0
	s_add_u32 s98, s98, 0x80
	s_addc_u32 s99, s99, 0
	s_add_i32 m0, s30, s39
	ds_read_b128 v[172:175], v248 offset:51200
	global_load_lds_dwordx4 v194, s[100:101]
	s_add_i32 m0, m0, 0x2000
	ds_read_b128 v[176:179], v248 offset:52224
	global_load_lds_dwordx4 v208, s[100:101]
	s_add_i32 m0, s31, s39
	ds_read_b128 v[180:183], v248 offset:53248
	global_load_lds_dwordx4 v194, s[28:29]
	s_add_i32 m0, m0, 0x2000
	ds_read_b128 v[184:187], v248 offset:54272
	global_load_lds_dwordx4 v208, s[28:29]
	s_mov_b32 m0, s46
	ds_read_b128 v[188:191], v248 offset:55296
	global_load_lds_dwordx4 v204, s[98:99]
	s_mov_b32 m0, s48
	ds_read_b128 v[214:217], v248 offset:56320
	global_load_lds_dwordx4 v206, s[98:99]
	s_waitcnt vmcnt(8)
	s_waitcnt lgkmcnt(0)
	s_setprio 1
	s_barrier
	v_mfma_f32_16x16x32_bf16 v[60:63], v[120:123], v[164:167], v[60:63]
	v_mfma_f32_16x16x32_bf16 v[56:59], v[132:135], v[164:167], v[56:59]
	v_mfma_f32_16x16x32_bf16 v[44:47], v[120:123], v[172:175], v[44:47]
	v_mfma_f32_16x16x32_bf16 v[40:43], v[132:135], v[172:175], v[40:43]
	v_mfma_f32_16x16x32_bf16 v[28:31], v[120:123], v[180:183], v[28:31]
	v_mfma_f32_16x16x32_bf16 v[24:27], v[132:135], v[180:183], v[24:27]
	v_mfma_f32_16x16x32_bf16 v[12:15], v[120:123], v[188:191], v[12:15]
	v_mfma_f32_16x16x32_bf16 v[8:11], v[132:135], v[188:191], v[8:11]
	v_mfma_f32_16x16x32_bf16 v[60:63], v[128:131], v[168:171], v[60:63]
	v_mfma_f32_16x16x32_bf16 v[56:59], v[136:139], v[168:171], v[56:59]
	v_mfma_f32_16x16x32_bf16 v[44:47], v[128:131], v[176:179], v[44:47]
	v_mfma_f32_16x16x32_bf16 v[40:43], v[136:139], v[176:179], v[40:43]
	v_mfma_f32_16x16x32_bf16 v[28:31], v[128:131], v[184:187], v[28:31]
	v_mfma_f32_16x16x32_bf16 v[24:27], v[136:139], v[184:187], v[24:27]
	v_mfma_f32_16x16x32_bf16 v[12:15], v[128:131], v[214:217], v[12:15]
	v_mfma_f32_16x16x32_bf16 v[8:11], v[136:139], v[214:217], v[8:11]
	v_mfma_f32_16x16x32_bf16 v[52:55], v[140:143], v[164:167], v[52:55]
	v_mfma_f32_16x16x32_bf16 v[48:51], v[156:159], v[164:167], v[48:51]
	v_mfma_f32_16x16x32_bf16 v[36:39], v[140:143], v[172:175], v[36:39]
	v_mfma_f32_16x16x32_bf16 v[32:35], v[156:159], v[172:175], v[32:35]
	v_mfma_f32_16x16x32_bf16 v[20:23], v[140:143], v[180:183], v[20:23]
	v_mfma_f32_16x16x32_bf16 v[16:19], v[156:159], v[180:183], v[16:19]
	v_mfma_f32_16x16x32_bf16 v[4:7], v[140:143], v[188:191], v[4:7]
	v_mfma_f32_16x16x32_bf16 v[0:3], v[156:159], v[188:191], v[0:3]
	v_mfma_f32_16x16x32_bf16 v[52:55], v[144:147], v[168:171], v[52:55]
	v_mfma_f32_16x16x32_bf16 v[48:51], v[160:163], v[168:171], v[48:51]
	v_mfma_f32_16x16x32_bf16 v[36:39], v[144:147], v[176:179], v[36:39]
	v_mfma_f32_16x16x32_bf16 v[32:35], v[160:163], v[176:179], v[32:35]
	v_mfma_f32_16x16x32_bf16 v[20:23], v[144:147], v[184:187], v[20:23]
	v_mfma_f32_16x16x32_bf16 v[16:19], v[160:163], v[184:187], v[16:19]
	v_mfma_f32_16x16x32_bf16 v[4:7], v[144:147], v[214:217], v[4:7]
	v_mfma_f32_16x16x32_bf16 v[0:3], v[160:163], v[214:217], v[0:3]
	s_setprio 0
	s_barrier
	s_add_i32 s56, s56, 2
	s_add_u32 s40, s40, 0x100
	s_addc_u32 s41, s41, 0
	s_cmp_gt_u32 s56, 61
	s_cbranch_scc0 .LBB0_965
	s_and_b64 vcc, exec, s[10:11]
	s_cbranch_vccz .LBB0_968
	s_barrier

; #define PG8_STAGE(bufoff, gbase, voff) do { _Pragma("unroll") for (int _i = 0; _i < 2; ++_i) \
;         __builtin_amdgcn_global_load_lds((const unsigned*)((const char*)(gbase) + (voff)[_i]), (PG8_LAS unsigned*)(lds + (bufoff) + ldsw + _i * 8192), 16, 0, 0); } while (0)
; #define PG8_LDA(dst, b, h) do { _Pragma("unroll") for (int m = 0; m < 4; ++m) _Pragma("unroll") for (int k = 0; k < 2; ++k) dst[m][k] = *(const PG8_LAS bf16x8*)(lds + PG8_SA(b, h) + aoff + m * 2048 + k * 1024); } while (0)
; #define PG8_LDB(dst, b, h) do { _Pragma("unroll") for (int n = 0; n < 2; ++n) _Pragma("unroll") for (int k = 0; k < 2; ++k) dst[n][k] = *(const PG8_LAS bf16x8*)(lds + PG8_SB(b, h) + boff + n * 2048 + k * 1024); } while (0)
; #define PG8_MMA(ai, bj, At, Bt) do { __builtin_amdgcn_s_setprio(1); _Pragma("unroll") for (int m = 0; m < 4; ++m) _Pragma("unroll") for (int n = 0; n < 2; ++n) _Pragma("unroll") for (int k = 0; k < 2; ++k) \
;         acc[ai][bj][m][n] = __builtin_amdgcn_mfma_f32_16x16x32_bf16(Bt[n][k], At[m][k], acc[ai][bj][m][n], 0, 0, 0); __builtin_amdgcn_s_setprio(0); } while (0)
; #define PG8_WAIT_L(n) asm volatile("s_waitcnt lgkmcnt(" #n ")" ::: "memory")
; template <class Epi, class Sched, bool ALIGN_EPI = false, bool SP2 = false>
; __device__ __forceinline__ void gemm_phase(PG8_LAS unsigned char* lds, const Gemm g, const Sched& S, const Epi& E) {
;     ...
;             const bool last = (t == nt - 2);
;             const char* a1 = cA + (size_t)(t + 1) * kstep;
;             const char* a2 = last ? nA : cA + (size_t)(t + 2) * kstep; const char* b2 = last ? nB : cB + (size_t)(t + 2) * kstep;
;             const char* a3 = a2 + kstep; const char* b3 = b2 + kstep;
;             if (last && has_next) S.a_ready(nxt);
;             if constexpr (SP2) {
;             const int rx = (relax && t == 0) ? 1 : 0;
;             PG8_STAGE(PG8_SA(1, 1), a1 + hstep, voffA); PG8_SCHED; PG8_LDB(B0, 0, 0); PG8_LDB(B1, 0, 1); PG8_SCHED; PG8_LDA(At, 0, 0);
;             PG8_WAIT_V8_UNLESS(rx); PG8_WAIT_L(0); PG8_BAR; PG8_MMA(0, 0, At, B0); PG8_MMA(0, 1, At, B1); PG8_BAR; PG8_SCHED;
;             PG8_STAGE(PG8_SB(0, 0), b2, voffB); PG8_STAGE(PG8_SB(0, 1), b2 + hstep, voffB); PG8_STAGE(PG8_SA(0, 0), a2, voffA); PG8_SCHED; PG8_LDA(At, 0, 1);
;             PG8_WAIT_V8_UNLESS(rx); PG8_WAIT_L(0); PG8_BAR; PG8_MMA(1, 0, At, B0); PG8_MMA(1, 1, At, B1); PG8_BAR; PG8_SCHED;
.LBB0_1133:
	s_add_u32 s28, s42, vcc_lo
	s_addc_u32 s29, s43, vcc_hi
	s_add_u32 s30, s28, 0x100
	s_addc_u32 s31, s29, 0
	s_add_u32 s98, s28, 0x40080
	s_addc_u32 s99, s29, 0
	s_add_u32 s65, s57, vcc_lo
	s_addc_u32 s66, s58, vcc_hi
	s_cmp_eq_u32 vcc_lo, 0
	s_cselect_b64 s[28:29], -1, 0
	s_and_b64 s[60:61], s[62:63], s[28:29]
	s_cmpk_eq_i32 vcc_lo, 0x700
	s_cselect_b32 s31, s19, s31
	s_cselect_b32 s30, s27, s30
	s_cselect_b32 s29, s17, s66
	s_cselect_b32 s28, s34, s65
	s_add_i32 s65, 0, 0x10000
	s_add_i32 s66, 0, 0x14000
	v_add_u32_e32 v144, s65, v174
	v_add_u32_e32 v172, s66, v174
	ds_read_b128 v[132:135], v144
	ds_read_b128 v[136:139], v144 offset:1024
	ds_read_b128 v[140:143], v144 offset:2048
	ds_read_b128 v[144:147], v144 offset:3072
	ds_read_b128 v[160:163], v172
	ds_read_b128 v[164:167], v172 offset:1024
	ds_read_b128 v[168:171], v172 offset:2048
	ds_read_b128 v[176:179], v172 offset:3072
	ds_read_b128 v[180:183], v175
	ds_read_b128 v[184:187], v175 offset:1024
	ds_read_b128 v[188:191], v175 offset:2048
	ds_read_b128 v[204:207], v175 offset:3072
	ds_read_b128 v[208:211], v175 offset:4096
	ds_read_b128 v[212:215], v175 offset:5120
	ds_read_b128 v[216:219], v175 offset:6144
	s_add_i32 m0, s41, 0xc000
	s_and_b32 s67, s60, 1
	global_load_lds_dwordx4 v148, s[98:99]
	s_add_i32 m0, s41, 0xe000
	ds_read_b128 v[220:223], v175 offset:7168
	global_load_lds_dwordx4 v152, s[98:99]
	s_cmp_lg_i32 s67, 0
	s_cbranch_scc1 .Lpg8rx10
	s_waitcnt vmcnt(8)
.Lpg8rx10:
	s_waitcnt lgkmcnt(0)
	s_setprio 1
	s_barrier
	v_mfma_f32_16x16x32_bf16 v[124:127], v[132:135], v[180:183], v[124:127]
	v_mfma_f32_16x16x32_bf16 v[120:123], v[140:143], v[180:183], v[120:123]
	v_mfma_f32_16x16x32_bf16 v[108:111], v[132:135], v[188:191], v[108:111]
	v_mfma_f32_16x16x32_bf16 v[104:107], v[140:143], v[188:191], v[104:107]
	v_mfma_f32_16x16x32_bf16 v[92:95], v[132:135], v[208:211], v[92:95]
	v_mfma_f32_16x16x32_bf16 v[88:91], v[140:143], v[208:211], v[88:91]
	v_mfma_f32_16x16x32_bf16 v[76:79], v[132:135], v[216:219], v[76:79]
	v_mfma_f32_16x16x32_bf16 v[72:75], v[140:143], v[216:219], v[72:75]
	v_mfma_f32_16x16x32_bf16 v[124:127], v[136:139], v[184:187], v[124:127]
	v_mfma_f32_16x16x32_bf16 v[120:123], v[144:147], v[184:187], v[120:123]
	v_mfma_f32_16x16x32_bf16 v[108:111], v[136:139], v[204:207], v[108:111]
	v_mfma_f32_16x16x32_bf16 v[104:107], v[144:147], v[204:207], v[104:107]
	v_mfma_f32_16x16x32_bf16 v[92:95], v[136:139], v[212:215], v[92:95]
	v_mfma_f32_16x16x32_bf16 v[88:91], v[144:147], v[212:215], v[88:91]
	v_mfma_f32_16x16x32_bf16 v[76:79], v[136:139], v[220:223], v[76:79]
	v_mfma_f32_16x16x32_bf16 v[72:75], v[144:147], v[220:223], v[72:75]
	v_mfma_f32_16x16x32_bf16 v[116:119], v[160:163], v[180:183], v[116:119]
	v_mfma_f32_16x16x32_bf16 v[112:115], v[168:171], v[180:183], v[112:115]
	v_mfma_f32_16x16x32_bf16 v[100:103], v[160:163], v[188:191], v[100:103]
	v_mfma_f32_16x16x32_bf16 v[96:99], v[168:171], v[188:191], v[96:99]
	v_mfma_f32_16x16x32_bf16 v[84:87], v[160:163], v[208:211], v[84:87]
	v_mfma_f32_16x16x32_bf16 v[80:83], v[168:171], v[208:211], v[80:83]
	v_mfma_f32_16x16x32_bf16 v[68:71], v[160:163], v[216:219], v[68:71]
	v_mfma_f32_16x16x32_bf16 v[64:67], v[168:171], v[216:219], v[64:67]
	v_mfma_f32_16x16x32_bf16 v[116:119], v[164:167], v[184:187], v[116:119]
	v_mfma_f32_16x16x32_bf16 v[112:115], v[176:179], v[184:187], v[112:115]
	v_mfma_f32_16x16x32_bf16 v[100:103], v[164:167], v[204:207], v[100:103]
	v_mfma_f32_16x16x32_bf16 v[96:99], v[176:179], v[204:207], v[96:99]
	v_mfma_f32_16x16x32_bf16 v[84:87], v[164:167], v[212:215], v[84:87]
	v_mfma_f32_16x16x32_bf16 v[80:83], v[176:179], v[212:215], v[80:83]
	v_mfma_f32_16x16x32_bf16 v[68:71], v[164:167], v[220:223], v[68:71]
	v_mfma_f32_16x16x32_bf16 v[64:67], v[176:179], v[220:223], v[64:67]
	s_setprio 0
	s_barrier
	ds_read_b128 v[180:183], v175 offset:16384
	ds_read_b128 v[184:187], v175 offset:17408
	s_add_u32 s60, s28, 0x40000
	s_addc_u32 s61, s29, 0
	s_add_i32 m0, s65, s35
	ds_read_b128 v[188:191], v175 offset:18432
	global_load_lds_dwordx4 v150, s[28:29]
	s_add_i32 m0, m0, 0x2000
	ds_read_b128 v[204:207], v175 offset:19456
	global_load_lds_dwordx4 v154, s[28:29]
	s_add_i32 m0, s66, s35
	ds_read_b128 v[208:211], v175 offset:20480
	global_load_lds_dwordx4 v150, s[60:61]
	s_add_i32 m0, m0, 0x2000
	ds_read_b128 v[212:215], v175 offset:21504
	global_load_lds_dwordx4 v154, s[60:61]
	s_mov_b32 m0, s41
	ds_read_b128 v[216:219], v175 offset:22528
	global_load_lds_dwordx4 v148, s[30:31]
	s_mov_b32 m0, s48
	ds_read_b128 v[220:223], v175 offset:23552
	global_load_lds_dwordx4 v152, s[30:31]
	s_cmp_lg_i32 s67, 0
	s_cbranch_scc1 .Lpg8rx11
	s_waitcnt vmcnt(8)
; #define PG8_STAGE(bufoff, gbase, voff) do { _Pragma("unroll") for (int _i = 0; _i < 2; ++_i) \
;         __builtin_amdgcn_global_load_lds((const unsigned*)((const char*)(gbase) + (voff)[_i]), (PG8_LAS unsigned*)(lds + (bufoff) + ldsw + _i * 8192), 16, 0, 0); } while (0)
; #define PG8_LDA(dst, b, h) do { _Pragma("unroll") for (int m = 0; m < 4; ++m) _Pragma("unroll") for (int k = 0; k < 2; ++k) dst[m][k] = *(const PG8_LAS bf16x8*)(lds + PG8_SA(b, h) + aoff + m * 2048 + k * 1024); } while (0)
; #define PG8_LDB(dst, b, h) do { _Pragma("unroll") for (int n = 0; n < 2; ++n) _Pragma("unroll") for (int k = 0; k < 2; ++k) dst[n][k] = *(const PG8_LAS bf16x8*)(lds + PG8_SB(b, h) + boff + n * 2048 + k * 1024); } while (0)
; #define PG8_MMA(ai, bj, At, Bt) do { __builtin_amdgcn_s_setprio(1); _Pragma("unroll") for (int m = 0; m < 4; ++m) _Pragma("unroll") for (int n = 0; n < 2; ++n) _Pragma("unroll") for (int k = 0; k < 2; ++k) \
;         acc[ai][bj][m][n] = __builtin_amdgcn_mfma_f32_16x16x32_bf16(Bt[n][k], At[m][k], acc[ai][bj][m][n], 0, 0, 0); __builtin_amdgcn_s_setprio(0); } while (0)
; #define PG8_WAIT_V(n) asm volatile("s_waitcnt vmcnt(" #n ")" ::: "memory")
; #define PG8_WAIT_L(n) asm volatile("s_waitcnt lgkmcnt(" #n ")" ::: "memory")
; #define PG8_WAIT_V8_UNLESS(flag) asm volatile("s_cmp_lg_i32 %0, 0\n\ts_cbranch_scc1 .Lpg8rx%=\n\ts_waitcnt vmcnt(8)\n.Lpg8rx%=:" :: "s"(__builtin_amdgcn_readfirstlane(flag)) : "scc", "memory")
; #define PG8_BAR __builtin_amdgcn_s_barrier()
; #define PG8_SCHED __builtin_amdgcn_sched_barrier(0)
; template <class Epi, class Sched, bool ALIGN_EPI = false, bool SP2 = false>
; __device__ __forceinline__ void gemm_phase(PG8_LAS unsigned char* lds, const Gemm g, const Sched& S, const Epi& E) {
;     ...
;             PG8_WAIT_V8_UNLESS(rx); PG8_WAIT_L(0); PG8_BAR; PG8_MMA(1, 0, At, B0); PG8_MMA(1, 1, At, B1); PG8_BAR; PG8_SCHED;
;             PG8_STAGE(PG8_SA(0, 1), a2 + hstep, voffA); PG8_SCHED; PG8_LDB(B0, 1, 0); PG8_LDB(B1, 1, 1); PG8_SCHED; PG8_LDA(At, 1, 0);
;             PG8_WAIT_V(8); PG8_WAIT_L(0); PG8_BAR; PG8_MMA(0, 0, At, B0); PG8_MMA(0, 1, At, B1); PG8_BAR; PG8_SCHED;
.Lpg8rx11:
	s_waitcnt lgkmcnt(0)
	s_setprio 1
	s_barrier
	v_mfma_f32_16x16x32_bf16 v[60:63], v[132:135], v[180:183], v[60:63]
	v_mfma_f32_16x16x32_bf16 v[56:59], v[140:143], v[180:183], v[56:59]
	v_mfma_f32_16x16x32_bf16 v[44:47], v[132:135], v[188:191], v[44:47]
	v_mfma_f32_16x16x32_bf16 v[40:43], v[140:143], v[188:191], v[40:43]
	v_mfma_f32_16x16x32_bf16 v[28:31], v[132:135], v[208:211], v[28:31]
	v_mfma_f32_16x16x32_bf16 v[24:27], v[140:143], v[208:211], v[24:27]
	v_mfma_f32_16x16x32_bf16 v[12:15], v[132:135], v[216:219], v[12:15]
	v_mfma_f32_16x16x32_bf16 v[8:11], v[140:143], v[216:219], v[8:11]
	v_mfma_f32_16x16x32_bf16 v[60:63], v[136:139], v[184:187], v[60:63]
	v_mfma_f32_16x16x32_bf16 v[56:59], v[144:147], v[184:187], v[56:59]
	v_mfma_f32_16x16x32_bf16 v[44:47], v[136:139], v[204:207], v[44:47]
	v_mfma_f32_16x16x32_bf16 v[40:43], v[144:147], v[204:207], v[40:43]
	v_mfma_f32_16x16x32_bf16 v[28:31], v[136:139], v[212:215], v[28:31]
	v_mfma_f32_16x16x32_bf16 v[24:27], v[144:147], v[212:215], v[24:27]
	v_mfma_f32_16x16x32_bf16 v[12:15], v[136:139], v[220:223], v[12:15]
	v_mfma_f32_16x16x32_bf16 v[8:11], v[144:147], v[220:223], v[8:11]
	v_mfma_f32_16x16x32_bf16 v[52:55], v[160:163], v[180:183], v[52:55]
	v_mfma_f32_16x16x32_bf16 v[48:51], v[168:171], v[180:183], v[48:51]
	v_mfma_f32_16x16x32_bf16 v[36:39], v[160:163], v[188:191], v[36:39]
	v_mfma_f32_16x16x32_bf16 v[32:35], v[168:171], v[188:191], v[32:35]
	v_mfma_f32_16x16x32_bf16 v[20:23], v[160:163], v[208:211], v[20:23]
	v_mfma_f32_16x16x32_bf16 v[16:19], v[168:171], v[208:211], v[16:19]
	v_mfma_f32_16x16x32_bf16 v[4:7], v[160:163], v[216:219], v[4:7]
	v_mfma_f32_16x16x32_bf16 v[0:3], v[168:171], v[216:219], v[0:3]
	v_mfma_f32_16x16x32_bf16 v[52:55], v[164:167], v[184:187], v[52:55]
	v_mfma_f32_16x16x32_bf16 v[48:51], v[176:179], v[184:187], v[48:51]
	v_mfma_f32_16x16x32_bf16 v[36:39], v[164:167], v[204:207], v[36:39]
	v_mfma_f32_16x16x32_bf16 v[32:35], v[176:179], v[204:207], v[32:35]
	v_mfma_f32_16x16x32_bf16 v[20:23], v[164:167], v[212:215], v[20:23]
	v_mfma_f32_16x16x32_bf16 v[16:19], v[176:179], v[212:215], v[16:19]
	v_mfma_f32_16x16x32_bf16 v[4:7], v[164:167], v[220:223], v[4:7]
	v_mfma_f32_16x16x32_bf16 v[0:3], v[176:179], v[220:223], v[0:3]
	s_setprio 0
	s_barrier
	s_mov_b64 s[98:99], s[30:31]
	s_add_u32 s100, s30, 0x40000
	s_addc_u32 s101, s31, 0
	s_add_i32 s30, 0, 0x18000
	s_add_i32 s31, 0, 0x1c000
	v_add_u32_e32 v144, s30, v174
	v_add_u32_e32 v176, s31, v174
	ds_read_b128 v[132:135], v144
	ds_read_b128 v[136:139], v144 offset:1024
	ds_read_b128 v[140:143], v144 offset:2048
	ds_read_b128 v[144:147], v144 offset:3072
	ds_read_b128 v[160:163], v176
	ds_read_b128 v[164:167], v176 offset:1024
	ds_read_b128 v[168:171], v176 offset:2048
	ds_read_b128 v[176:179], v176 offset:3072
	ds_read_b128 v[180:183], v175 offset:32768
	ds_read_b128 v[184:187], v175 offset:33792
	ds_read_b128 v[188:191], v175 offset:34816
	ds_read_b128 v[204:207], v175 offset:35840
	ds_read_b128 v[208:211], v175 offset:36864
	ds_read_b128 v[212:215], v175 offset:37888
	s_mov_b32 m0, s50
	ds_read_b128 v[216:219], v175 offset:38912
	global_load_lds_dwordx4 v148, s[100:101]
	s_mov_b32 m0, s51
	ds_read_b128 v[220:223], v175 offset:39936
	global_load_lds_dwordx4 v152, s[100:101]
	s_waitcnt vmcnt(8)
	s_waitcnt lgkmcnt(0)
	s_setprio 1
	s_barrier
	v_mfma_f32_16x16x32_bf16 v[124:127], v[132:135], v[180:183], v[124:127]
	v_mfma_f32_16x16x32_bf16 v[120:123], v[140:143], v[180:183], v[120:123]
	v_mfma_f32_16x16x32_bf16 v[108:111], v[132:135], v[188:191], v[108:111]
	v_mfma_f32_16x16x32_bf16 v[104:107], v[140:143], v[188:191], v[104:107]
	v_mfma_f32_16x16x32_bf16 v[92:95], v[132:135], v[208:211], v[92:95]
	v_mfma_f32_16x16x32_bf16 v[88:91], v[140:143], v[208:211], v[88:91]
	v_mfma_f32_16x16x32_bf16 v[76:79], v[132:135], v[216:219], v[76:79]
	v_mfma_f32_16x16x32_bf16 v[72:75], v[140:143], v[216:219], v[72:75]
	v_mfma_f32_16x16x32_bf16 v[124:127], v[136:139], v[184:187], v[124:127]
	v_mfma_f32_16x16x32_bf16 v[120:123], v[144:147], v[184:187], v[120:123]
	v_mfma_f32_16x16x32_bf16 v[108:111], v[136:139], v[204:207], v[108:111]
	v_mfma_f32_16x16x32_bf16 v[104:107], v[144:147], v[204:207], v[104:107]
	v_mfma_f32_16x16x32_bf16 v[92:95], v[136:139], v[212:215], v[92:95]
	v_mfma_f32_16x16x32_bf16 v[88:91], v[144:147], v[212:215], v[88:91]
	v_mfma_f32_16x16x32_bf16 v[76:79], v[136:139], v[220:223], v[76:79]
	v_mfma_f32_16x16x32_bf16 v[72:75], v[144:147], v[220:223], v[72:75]
	v_mfma_f32_16x16x32_bf16 v[116:119], v[160:163], v[180:183], v[116:119]
	v_mfma_f32_16x16x32_bf16 v[112:115], v[168:171], v[180:183], v[112:115]
	v_mfma_f32_16x16x32_bf16 v[100:103], v[160:163], v[188:191], v[100:103]
	v_mfma_f32_16x16x32_bf16 v[96:99], v[168:171], v[188:191], v[96:99]
	v_mfma_f32_16x16x32_bf16 v[84:87], v[160:163], v[208:211], v[84:87]
	v_mfma_f32_16x16x32_bf16 v[80:83], v[168:171], v[208:211], v[80:83]
	v_mfma_f32_16x16x32_bf16 v[68:71], v[160:163], v[216:219], v[68:71]
	v_mfma_f32_16x16x32_bf16 v[64:67], v[168:171], v[216:219], v[64:67]
	v_mfma_f32_16x16x32_bf16 v[116:119], v[164:167], v[184:187], v[116:119]
	v_mfma_f32_16x16x32_bf16 v[112:115], v[176:179], v[184:187], v[112:115]
	v_mfma_f32_16x16x32_bf16 v[100:103], v[164:167], v[204:207], v[100:103]
	v_mfma_f32_16x16x32_bf16 v[96:99], v[176:179], v[204:207], v[96:99]
	v_mfma_f32_16x16x32_bf16 v[84:87], v[164:167], v[212:215], v[84:87]
	v_mfma_f32_16x16x32_bf16 v[80:83], v[176:179], v[212:215], v[80:83]
	v_mfma_f32_16x16x32_bf16 v[68:71], v[164:167], v[220:223], v[68:71]
	v_mfma_f32_16x16x32_bf16 v[64:67], v[176:179], v[220:223], v[64:67]
	s_setprio 0
	s_barrier
; #define PG8_STAGE(bufoff, gbase, voff) do { _Pragma("unroll") for (int _i = 0; _i < 2; ++_i) \
;         __builtin_amdgcn_global_load_lds((const unsigned*)((const char*)(gbase) + (voff)[_i]), (PG8_LAS unsigned*)(lds + (bufoff) + ldsw + _i * 8192), 16, 0, 0); } while (0)
; #define PG8_LDA(dst, b, h) do { _Pragma("unroll") for (int m = 0; m < 4; ++m) _Pragma("unroll") for (int k = 0; k < 2; ++k) dst[m][k] = *(const PG8_LAS bf16x8*)(lds + PG8_SA(b, h) + aoff + m * 2048 + k * 1024); } while (0)
; #define PG8_MMA(ai, bj, At, Bt) do { __builtin_amdgcn_s_setprio(1); _Pragma("unroll") for (int m = 0; m < 4; ++m) _Pragma("unroll") for (int n = 0; n < 2; ++n) _Pragma("unroll") for (int k = 0; k < 2; ++k) \
;         acc[ai][bj][m][n] = __builtin_amdgcn_mfma_f32_16x16x32_bf16(Bt[n][k], At[m][k], acc[ai][bj][m][n], 0, 0, 0); __builtin_amdgcn_s_setprio(0); } while (0)
; #define PG8_WAIT_V(n) asm volatile("s_waitcnt vmcnt(" #n ")" ::: "memory")
; #define PG8_WAIT_L(n) asm volatile("s_waitcnt lgkmcnt(" #n ")" ::: "memory")
; #define PG8_BAR __builtin_amdgcn_s_barrier()
; #define PG8_SCHED __builtin_amdgcn_sched_barrier(0)
; template <class Epi, class Sched, bool ALIGN_EPI = false, bool SP2 = false>
; __device__ __forceinline__ void gemm_phase(PG8_LAS unsigned char* lds, const Gemm g, const Sched& S, const Epi& E) {
;     ...
;             PG8_STAGE(PG8_SB(1, 0), b3, voffB); PG8_STAGE(PG8_SB(1, 1), b3 + hstep, voffB); PG8_STAGE(PG8_SA(1, 0), a3, voffA); PG8_SCHED; PG8_LDA(At, 1, 1);
;             PG8_WAIT_V(8); PG8_WAIT_L(0); PG8_BAR; PG8_MMA(1, 0, At, B0); PG8_MMA(1, 1, At, B1); PG8_BAR; PG8_SCHED;
;     ...
;         if constexpr (ALIGN_EPI) { if (wr == 0) PG8_BAR; }
	ds_read_b128 v[180:183], v175 offset:49152
	ds_read_b128 v[184:187], v175 offset:50176
	s_add_u32 s100, s28, 0x80
	s_addc_u32 s101, s29, 0
	s_add_u32 s28, s28, 0x40080
	s_addc_u32 s29, s29, 0
	s_add_u32 s98, s98, 0x80
	s_addc_u32 s99, s99, 0
	s_add_i32 m0, s30, s35
	ds_read_b128 v[188:191], v175 offset:51200
	global_load_lds_dwordx4 v150, s[100:101]
	s_add_i32 m0, m0, 0x2000
	ds_read_b128 v[204:207], v175 offset:52224
	global_load_lds_dwordx4 v154, s[100:101]
	s_add_i32 m0, s31, s35
	ds_read_b128 v[208:211], v175 offset:53248
	global_load_lds_dwordx4 v150, s[28:29]
	s_add_i32 m0, m0, 0x2000
	ds_read_b128 v[212:215], v175 offset:54272
	global_load_lds_dwordx4 v154, s[28:29]
	s_mov_b32 m0, s52
	ds_read_b128 v[216:219], v175 offset:55296
	global_load_lds_dwordx4 v148, s[98:99]
	s_mov_b32 m0, s53
	ds_read_b128 v[220:223], v175 offset:56320
	global_load_lds_dwordx4 v152, s[98:99]
	s_waitcnt vmcnt(8)
	s_waitcnt lgkmcnt(0)
	s_setprio 1
	s_barrier
	v_mfma_f32_16x16x32_bf16 v[60:63], v[132:135], v[180:183], v[60:63]
	v_mfma_f32_16x16x32_bf16 v[56:59], v[140:143], v[180:183], v[56:59]
	v_mfma_f32_16x16x32_bf16 v[44:47], v[132:135], v[188:191], v[44:47]
	v_mfma_f32_16x16x32_bf16 v[40:43], v[140:143], v[188:191], v[40:43]
	v_mfma_f32_16x16x32_bf16 v[28:31], v[132:135], v[208:211], v[28:31]
	v_mfma_f32_16x16x32_bf16 v[24:27], v[140:143], v[208:211], v[24:27]
	v_mfma_f32_16x16x32_bf16 v[12:15], v[132:135], v[216:219], v[12:15]
	v_mfma_f32_16x16x32_bf16 v[8:11], v[140:143], v[216:219], v[8:11]
	v_mfma_f32_16x16x32_bf16 v[60:63], v[136:139], v[184:187], v[60:63]
	v_mfma_f32_16x16x32_bf16 v[56:59], v[144:147], v[184:187], v[56:59]
	v_mfma_f32_16x16x32_bf16 v[44:47], v[136:139], v[204:207], v[44:47]
	v_mfma_f32_16x16x32_bf16 v[40:43], v[144:147], v[204:207], v[40:43]
	v_mfma_f32_16x16x32_bf16 v[28:31], v[136:139], v[212:215], v[28:31]
	v_mfma_f32_16x16x32_bf16 v[24:27], v[144:147], v[212:215], v[24:27]
	v_mfma_f32_16x16x32_bf16 v[12:15], v[136:139], v[220:223], v[12:15]
	v_mfma_f32_16x16x32_bf16 v[8:11], v[144:147], v[220:223], v[8:11]
	v_mfma_f32_16x16x32_bf16 v[52:55], v[160:163], v[180:183], v[52:55]
	v_mfma_f32_16x16x32_bf16 v[48:51], v[168:171], v[180:183], v[48:51]
	v_mfma_f32_16x16x32_bf16 v[36:39], v[160:163], v[188:191], v[36:39]
	v_mfma_f32_16x16x32_bf16 v[32:35], v[168:171], v[188:191], v[32:35]
	v_mfma_f32_16x16x32_bf16 v[20:23], v[160:163], v[208:211], v[20:23]
	v_mfma_f32_16x16x32_bf16 v[16:19], v[168:171], v[208:211], v[16:19]
	v_mfma_f32_16x16x32_bf16 v[4:7], v[160:163], v[216:219], v[4:7]
	v_mfma_f32_16x16x32_bf16 v[0:3], v[168:171], v[216:219], v[0:3]
	v_mfma_f32_16x16x32_bf16 v[52:55], v[164:167], v[184:187], v[52:55]
	v_mfma_f32_16x16x32_bf16 v[48:51], v[176:179], v[184:187], v[48:51]
	v_mfma_f32_16x16x32_bf16 v[36:39], v[164:167], v[204:207], v[36:39]
	v_mfma_f32_16x16x32_bf16 v[32:35], v[176:179], v[204:207], v[32:35]
	v_mfma_f32_16x16x32_bf16 v[20:23], v[164:167], v[212:215], v[20:23]
	v_mfma_f32_16x16x32_bf16 v[16:19], v[176:179], v[212:215], v[16:19]
	v_mfma_f32_16x16x32_bf16 v[4:7], v[164:167], v[220:223], v[4:7]
	v_mfma_f32_16x16x32_bf16 v[0:3], v[176:179], v[220:223], v[0:3]
	s_setprio 0
	s_barrier
	s_add_i32 s59, s59, 2
	s_add_u32 vcc_lo, vcc_lo, 0x100
	s_addc_u32 vcc_hi, vcc_hi, 0
	s_cmp_gt_u32 s59, 13
	s_cbranch_scc0 .LBB0_1133
	s_and_b64 vcc, exec, s[14:15]
	s_cbranch_vccz .LBB0_1136
	s_barrier
